# per-cluster s_setprio flips removed from all five GEMM K-loops (on top of epilogue/attention load hoists)
# speedup vs baseline: 1.0127x; 1.0008x over previous
; #define PG8_STAGE(bufoff, gbase, voff) do { _Pragma("unroll") for (int _i = 0; _i < 2; ++_i) \
;         __builtin_amdgcn_global_load_lds((const unsigned*)((const char*)(gbase) + (voff)[_i]), (PG8_LAS unsigned*)(lds + (bufoff) + ldsw + _i * 8192), 16, 0, 0); } while (0)
; #define PG8_LDA(dst, b, h) do { _Pragma("unroll") for (int m = 0; m < 4; ++m) _Pragma("unroll") for (int k = 0; k < 2; ++k) dst[m][k] = *(const PG8_LAS bf16x8*)(lds + PG8_SA(b, h) + aoff + m * 2048 + k * 1024); } while (0)
; #define PG8_LDB(dst, b, h) do { _Pragma("unroll") for (int n = 0; n < 2; ++n) _Pragma("unroll") for (int k = 0; k < 2; ++k) dst[n][k] = *(const PG8_LAS bf16x8*)(lds + PG8_SB(b, h) + boff + n * 2048 + k * 1024); } while (0)
; #define PG8_MMA(ai, bj, At, Bt) do { __builtin_amdgcn_s_setprio(1); _Pragma("unroll") for (int m = 0; m < 4; ++m) _Pragma("unroll") for (int n = 0; n < 2; ++n) _Pragma("unroll") for (int k = 0; k < 2; ++k) \
;         acc[ai][bj][m][n] = __builtin_amdgcn_mfma_f32_16x16x32_bf16(Bt[n][k], At[m][k], acc[ai][bj][m][n], 0, 0, 0); __builtin_amdgcn_s_setprio(0); } while (0)
; #define PG8_WAIT_V(n) asm volatile("s_waitcnt vmcnt(" #n ")" ::: "memory")
; #define PG8_WAIT_L(n) asm volatile("s_waitcnt lgkmcnt(" #n ")" ::: "memory")
; #define PG8_BAR __builtin_amdgcn_s_barrier()
; #define PG8_SCHED __builtin_amdgcn_sched_barrier(0)
; template <class Epi, class Sched, bool ALIGN_EPI = false, bool SP2 = false>
; __device__ __forceinline__ void gemm_phase(PG8_LAS unsigned char* lds, const Gemm g, const Sched& S, const Epi& E) {
;     ...
;             PG8_LDB(B0, 0, 0); PG8_LDB(B1, 0, 1); PG8_SCHED; PG8_LDA(At, 0, 0); PG8_STAGE(PG8_SA(1, 1), a1 + hstep, voffA);
;             PG8_WAIT_V(8); PG8_WAIT_L(0); PG8_BAR; PG8_MMA(0, 0, At, B0); PG8_MMA(0, 1, At, B1); PG8_BAR; PG8_SCHED;
;             PG8_LDA(At, 0, 1); PG8_STAGE(PG8_SB(0, 0), b2, voffB); PG8_STAGE(PG8_SB(0, 1), b2 + hstep, voffB); PG8_STAGE(PG8_SA(0, 0), a2, voffA);
;             PG8_WAIT_V(8); PG8_WAIT_L(0); PG8_BAR; PG8_MMA(1, 0, At, B0); PG8_MMA(1, 1, At, B1); PG8_BAR; PG8_SCHED;
.LBB0_143:
	s_add_u32 s56, s4, 0xfffc0080
	s_addc_u32 s57, s5, -1
	s_add_i32 s63, 0, 0x10000
	s_cmp_eq_u32 s62, 12
	s_cselect_b32 s59, s31, s57
	s_cselect_b32 s58, s33, s56
	s_cselect_b32 s57, s34, s51
	s_cselect_b32 s56, s35, s49
	s_add_i32 s66, 0, 0x14000
	v_add_u32_e32 v140, s63, v249
	v_add_u32_e32 v156, s66, v249
	ds_read_b128 v[128:131], v140
	ds_read_b128 v[132:135], v140 offset:1024
	ds_read_b128 v[136:139], v140 offset:2048
	ds_read_b128 v[140:143], v140 offset:3072
	ds_read_b128 v[144:147], v156
	ds_read_b128 v[148:151], v156 offset:1024
	ds_read_b128 v[152:155], v156 offset:2048
	ds_read_b128 v[156:159], v156 offset:3072
	v_lshl_add_u64 v[178:179], s[4:5], 0, v[206:207]
	s_add_i32 m0, s11, 0xc000
	ds_read_b128 v[160:163], v245
	ds_read_b128 v[164:167], v245 offset:1024
	ds_read_b128 v[168:171], v245 offset:2048
	ds_read_b128 v[172:175], v245 offset:3072
	ds_read_b128 v[208:211], v245 offset:4096
	ds_read_b128 v[212:215], v245 offset:5120
	ds_read_b128 v[216:219], v245 offset:6144
	ds_read_b128 v[220:223], v245 offset:7168
	global_load_lds_dwordx4 v[178:179], off
	v_lshl_add_u64 v[178:179], s[4:5], 0, v[204:205]
	s_add_i32 m0, s11, 0xe000
	s_nop 0
	global_load_lds_dwordx4 v[178:179], off
	s_waitcnt vmcnt(8)
	s_waitcnt lgkmcnt(0)
	s_barrier
	s_waitcnt lgkmcnt(0)
	v_mfma_f32_16x16x32_bf16 v[124:127], v[128:131], v[160:163], v[124:127]
	v_mfma_f32_16x16x32_bf16 v[120:123], v[136:139], v[160:163], v[120:123]
	v_mfma_f32_16x16x32_bf16 v[108:111], v[128:131], v[168:171], v[108:111]
	v_mfma_f32_16x16x32_bf16 v[104:107], v[136:139], v[168:171], v[104:107]
	v_mfma_f32_16x16x32_bf16 v[92:95], v[128:131], v[208:211], v[92:95]
	v_mfma_f32_16x16x32_bf16 v[88:91], v[136:139], v[208:211], v[88:91]
	v_mfma_f32_16x16x32_bf16 v[76:79], v[128:131], v[216:219], v[76:79]
	v_mfma_f32_16x16x32_bf16 v[72:75], v[136:139], v[216:219], v[72:75]
	v_mfma_f32_16x16x32_bf16 v[124:127], v[132:135], v[164:167], v[124:127]
	v_mfma_f32_16x16x32_bf16 v[120:123], v[140:143], v[164:167], v[120:123]
	v_mfma_f32_16x16x32_bf16 v[108:111], v[132:135], v[172:175], v[108:111]
	v_mfma_f32_16x16x32_bf16 v[104:107], v[140:143], v[172:175], v[104:107]
	v_mfma_f32_16x16x32_bf16 v[92:95], v[132:135], v[212:215], v[92:95]
	v_mfma_f32_16x16x32_bf16 v[88:91], v[140:143], v[212:215], v[88:91]
	v_mfma_f32_16x16x32_bf16 v[76:79], v[132:135], v[220:223], v[76:79]
	v_mfma_f32_16x16x32_bf16 v[72:75], v[140:143], v[220:223], v[72:75]
	v_mfma_f32_16x16x32_bf16 v[116:119], v[144:147], v[160:163], v[116:119]
	v_mfma_f32_16x16x32_bf16 v[112:115], v[152:155], v[160:163], v[112:115]
	v_mfma_f32_16x16x32_bf16 v[100:103], v[144:147], v[168:171], v[100:103]
	v_mfma_f32_16x16x32_bf16 v[96:99], v[152:155], v[168:171], v[96:99]
	v_mfma_f32_16x16x32_bf16 v[84:87], v[144:147], v[208:211], v[84:87]
	v_mfma_f32_16x16x32_bf16 v[80:83], v[152:155], v[208:211], v[80:83]
	v_mfma_f32_16x16x32_bf16 v[68:71], v[144:147], v[216:219], v[68:71]
	v_mfma_f32_16x16x32_bf16 v[64:67], v[152:155], v[216:219], v[64:67]
	v_mfma_f32_16x16x32_bf16 v[116:119], v[148:151], v[164:167], v[116:119]
	v_mfma_f32_16x16x32_bf16 v[112:115], v[156:159], v[164:167], v[112:115]
	v_mfma_f32_16x16x32_bf16 v[100:103], v[148:151], v[172:175], v[100:103]
	v_mfma_f32_16x16x32_bf16 v[96:99], v[156:159], v[172:175], v[96:99]
	v_mfma_f32_16x16x32_bf16 v[84:87], v[148:151], v[212:215], v[84:87]
	v_mfma_f32_16x16x32_bf16 v[80:83], v[156:159], v[212:215], v[80:83]
	v_mfma_f32_16x16x32_bf16 v[68:71], v[148:151], v[220:223], v[68:71]
	v_mfma_f32_16x16x32_bf16 v[64:67], v[156:159], v[220:223], v[64:67]
	s_barrier
	s_add_i32 s63, s63, s2
	v_lshl_add_u64 v[178:179], s[56:57], 0, v[198:199]
	s_mov_b32 m0, s63
	ds_read_b128 v[160:163], v245 offset:16384
	ds_read_b128 v[164:167], v245 offset:17408
	ds_read_b128 v[168:171], v245 offset:18432
	ds_read_b128 v[172:175], v245 offset:19456
	ds_read_b128 v[208:211], v245 offset:20480
	ds_read_b128 v[212:215], v245 offset:21504
	ds_read_b128 v[216:219], v245 offset:22528
	ds_read_b128 v[220:223], v245 offset:23552
	global_load_lds_dwordx4 v[178:179], off
	s_add_i32 m0, s63, 0x2000
	s_add_u32 s64, s56, 0x40000
	v_lshl_add_u64 v[224:225], s[56:57], 0, v[194:195]
	s_addc_u32 s65, s57, 0
	s_add_i32 s63, s66, s2
	global_load_lds_dwordx4 v[224:225], off
	v_lshl_add_u64 v[226:227], s[64:65], 0, v[198:199]
	s_mov_b32 m0, s63
	v_lshl_add_u64 v[228:229], s[58:59], 0, v[196:197]
	global_load_lds_dwordx4 v[226:227], off
	v_lshl_add_u64 v[226:227], s[64:65], 0, v[194:195]
	s_add_i32 m0, s63, 0x2000
	s_nop 0
	global_load_lds_dwordx4 v[226:227], off
	v_lshl_add_u64 v[226:227], s[58:59], 0, v[200:201]
	s_mov_b32 m0, s11
	s_nop 0
	global_load_lds_dwordx4 v[226:227], off
	s_mov_b32 m0, s20
	s_nop 0
	global_load_lds_dwordx4 v[228:229], off
	s_waitcnt vmcnt(8)
	s_waitcnt lgkmcnt(0)
	s_barrier
; #define PG8_STAGE(bufoff, gbase, voff) do { _Pragma("unroll") for (int _i = 0; _i < 2; ++_i) \
;         __builtin_amdgcn_global_load_lds((const unsigned*)((const char*)(gbase) + (voff)[_i]), (PG8_LAS unsigned*)(lds + (bufoff) + ldsw + _i * 8192), 16, 0, 0); } while (0)
; #define PG8_LDA(dst, b, h) do { _Pragma("unroll") for (int m = 0; m < 4; ++m) _Pragma("unroll") for (int k = 0; k < 2; ++k) dst[m][k] = *(const PG8_LAS bf16x8*)(lds + PG8_SA(b, h) + aoff + m * 2048 + k * 1024); } while (0)
; #define PG8_LDB(dst, b, h) do { _Pragma("unroll") for (int n = 0; n < 2; ++n) _Pragma("unroll") for (int k = 0; k < 2; ++k) dst[n][k] = *(const PG8_LAS bf16x8*)(lds + PG8_SB(b, h) + boff + n * 2048 + k * 1024); } while (0)
; #define PG8_MMA(ai, bj, At, Bt) do { __builtin_amdgcn_s_setprio(1); _Pragma("unroll") for (int m = 0; m < 4; ++m) _Pragma("unroll") for (int n = 0; n < 2; ++n) _Pragma("unroll") for (int k = 0; k < 2; ++k) \
;         acc[ai][bj][m][n] = __builtin_amdgcn_mfma_f32_16x16x32_bf16(Bt[n][k], At[m][k], acc[ai][bj][m][n], 0, 0, 0); __builtin_amdgcn_s_setprio(0); } while (0)
; #define PG8_WAIT_V(n) asm volatile("s_waitcnt vmcnt(" #n ")" ::: "memory")
; #define PG8_WAIT_L(n) asm volatile("s_waitcnt lgkmcnt(" #n ")" ::: "memory")
; #define PG8_BAR __builtin_amdgcn_s_barrier()
; #define PG8_SCHED __builtin_amdgcn_sched_barrier(0)
; template <class Epi, class Sched, bool ALIGN_EPI = false, bool SP2 = false>
; __device__ __forceinline__ void gemm_phase(PG8_LAS unsigned char* lds, const Gemm g, const Sched& S, const Epi& E) {
;     ...
;             PG8_WAIT_V(8); PG8_WAIT_L(0); PG8_BAR; PG8_MMA(1, 0, At, B0); PG8_MMA(1, 1, At, B1); PG8_BAR; PG8_SCHED;
;             PG8_LDB(B0, 1, 0); PG8_LDB(B1, 1, 1); PG8_SCHED; PG8_LDA(At, 1, 0); PG8_STAGE(PG8_SA(0, 1), a2 + hstep, voffA);
;             PG8_WAIT_V(8); PG8_WAIT_L(0); PG8_BAR; PG8_MMA(0, 0, At, B0); PG8_MMA(0, 1, At, B1); PG8_BAR; PG8_SCHED;
	s_waitcnt lgkmcnt(0)
	v_mfma_f32_16x16x32_bf16 v[60:63], v[128:131], v[160:163], v[60:63]
	v_mfma_f32_16x16x32_bf16 v[56:59], v[136:139], v[160:163], v[56:59]
	v_mfma_f32_16x16x32_bf16 v[48:51], v[128:131], v[168:171], v[48:51]
	v_mfma_f32_16x16x32_bf16 v[40:43], v[136:139], v[168:171], v[40:43]
	v_mfma_f32_16x16x32_bf16 v[32:35], v[128:131], v[208:211], v[32:35]
	v_mfma_f32_16x16x32_bf16 v[24:27], v[136:139], v[208:211], v[24:27]
	v_mfma_f32_16x16x32_bf16 v[16:19], v[128:131], v[216:219], v[16:19]
	v_mfma_f32_16x16x32_bf16 v[8:11], v[136:139], v[216:219], v[8:11]
	v_mfma_f32_16x16x32_bf16 v[60:63], v[132:135], v[164:167], v[60:63]
	v_mfma_f32_16x16x32_bf16 v[56:59], v[140:143], v[164:167], v[56:59]
	v_mfma_f32_16x16x32_bf16 v[48:51], v[132:135], v[172:175], v[48:51]
	v_mfma_f32_16x16x32_bf16 v[40:43], v[140:143], v[172:175], v[40:43]
	v_mfma_f32_16x16x32_bf16 v[32:35], v[132:135], v[212:215], v[32:35]
	v_mfma_f32_16x16x32_bf16 v[24:27], v[140:143], v[212:215], v[24:27]
	v_mfma_f32_16x16x32_bf16 v[16:19], v[132:135], v[220:223], v[16:19]
	v_mfma_f32_16x16x32_bf16 v[8:11], v[140:143], v[220:223], v[8:11]
	v_mfma_f32_16x16x32_bf16 v[52:55], v[144:147], v[160:163], v[52:55]
	v_mfma_f32_16x16x32_bf16 v[44:47], v[152:155], v[160:163], v[44:47]
	v_mfma_f32_16x16x32_bf16 v[36:39], v[144:147], v[168:171], v[36:39]
	v_mfma_f32_16x16x32_bf16 v[28:31], v[152:155], v[168:171], v[28:31]
	v_mfma_f32_16x16x32_bf16 v[20:23], v[144:147], v[208:211], v[20:23]
	v_mfma_f32_16x16x32_bf16 v[12:15], v[152:155], v[208:211], v[12:15]
	v_mfma_f32_16x16x32_bf16 v[4:7], v[144:147], v[216:219], v[4:7]
	v_mfma_f32_16x16x32_bf16 v[0:3], v[152:155], v[216:219], v[0:3]
	v_mfma_f32_16x16x32_bf16 v[52:55], v[148:151], v[164:167], v[52:55]
	v_mfma_f32_16x16x32_bf16 v[44:47], v[156:159], v[164:167], v[44:47]
	v_mfma_f32_16x16x32_bf16 v[36:39], v[148:151], v[172:175], v[36:39]
	v_mfma_f32_16x16x32_bf16 v[28:31], v[156:159], v[172:175], v[28:31]
	v_mfma_f32_16x16x32_bf16 v[20:23], v[148:151], v[212:215], v[20:23]
	v_mfma_f32_16x16x32_bf16 v[12:15], v[156:159], v[212:215], v[12:15]
	v_mfma_f32_16x16x32_bf16 v[4:7], v[148:151], v[220:223], v[4:7]
	v_mfma_f32_16x16x32_bf16 v[0:3], v[156:159], v[220:223], v[0:3]
	s_barrier
	s_add_i32 s63, 0, 0x18000
	s_add_i32 s64, 0, 0x1c000
	v_add_u32_e32 v140, s63, v249
	v_add_u32_e32 v156, s64, v249
	ds_read_b128 v[128:131], v140
	ds_read_b128 v[132:135], v140 offset:1024
	ds_read_b128 v[136:139], v140 offset:2048
	ds_read_b128 v[140:143], v140 offset:3072
	ds_read_b128 v[144:147], v156
	ds_read_b128 v[148:151], v156 offset:1024
	ds_read_b128 v[152:155], v156 offset:2048
	ds_read_b128 v[156:159], v156 offset:3072
	s_add_u32 s58, s58, 0x40000
	s_addc_u32 s59, s59, 0
	s_mov_b32 m0, s21
	v_lshl_add_u64 v[230:231], s[58:59], 0, v[200:201]
	ds_read_b128 v[160:163], v245 offset:32768
	ds_read_b128 v[164:167], v245 offset:33792
	ds_read_b128 v[168:171], v245 offset:34816
	ds_read_b128 v[172:175], v245 offset:35840
	ds_read_b128 v[208:211], v245 offset:36864
	ds_read_b128 v[212:215], v245 offset:37888
	ds_read_b128 v[216:219], v245 offset:38912
	ds_read_b128 v[220:223], v245 offset:39936
	global_load_lds_dwordx4 v[230:231], off
	v_lshl_add_u64 v[230:231], s[58:59], 0, v[196:197]
	s_mov_b32 m0, s22
	s_nop 0
	global_load_lds_dwordx4 v[230:231], off
	s_waitcnt vmcnt(8)
	s_waitcnt lgkmcnt(0)
	s_barrier
	s_waitcnt lgkmcnt(0)
	v_mfma_f32_16x16x32_bf16 v[124:127], v[128:131], v[160:163], v[124:127]
	v_mfma_f32_16x16x32_bf16 v[120:123], v[136:139], v[160:163], v[120:123]
	v_mfma_f32_16x16x32_bf16 v[108:111], v[128:131], v[168:171], v[108:111]
	v_mfma_f32_16x16x32_bf16 v[104:107], v[136:139], v[168:171], v[104:107]
	v_mfma_f32_16x16x32_bf16 v[92:95], v[128:131], v[208:211], v[92:95]
	v_mfma_f32_16x16x32_bf16 v[88:91], v[136:139], v[208:211], v[88:91]
	v_mfma_f32_16x16x32_bf16 v[76:79], v[128:131], v[216:219], v[76:79]
	v_mfma_f32_16x16x32_bf16 v[72:75], v[136:139], v[216:219], v[72:75]
	v_mfma_f32_16x16x32_bf16 v[124:127], v[132:135], v[164:167], v[124:127]
	v_mfma_f32_16x16x32_bf16 v[120:123], v[140:143], v[164:167], v[120:123]
	v_mfma_f32_16x16x32_bf16 v[108:111], v[132:135], v[172:175], v[108:111]
	v_mfma_f32_16x16x32_bf16 v[104:107], v[140:143], v[172:175], v[104:107]
	v_mfma_f32_16x16x32_bf16 v[92:95], v[132:135], v[212:215], v[92:95]
	v_mfma_f32_16x16x32_bf16 v[88:91], v[140:143], v[212:215], v[88:91]
	v_mfma_f32_16x16x32_bf16 v[76:79], v[132:135], v[220:223], v[76:79]
	v_mfma_f32_16x16x32_bf16 v[72:75], v[140:143], v[220:223], v[72:75]
	v_mfma_f32_16x16x32_bf16 v[116:119], v[144:147], v[160:163], v[116:119]
	v_mfma_f32_16x16x32_bf16 v[112:115], v[152:155], v[160:163], v[112:115]
	v_mfma_f32_16x16x32_bf16 v[100:103], v[144:147], v[168:171], v[100:103]
	v_mfma_f32_16x16x32_bf16 v[96:99], v[152:155], v[168:171], v[96:99]
	v_mfma_f32_16x16x32_bf16 v[84:87], v[144:147], v[208:211], v[84:87]
	v_mfma_f32_16x16x32_bf16 v[80:83], v[152:155], v[208:211], v[80:83]
	v_mfma_f32_16x16x32_bf16 v[68:71], v[144:147], v[216:219], v[68:71]
	v_mfma_f32_16x16x32_bf16 v[64:67], v[152:155], v[216:219], v[64:67]
	v_mfma_f32_16x16x32_bf16 v[116:119], v[148:151], v[164:167], v[116:119]
	v_mfma_f32_16x16x32_bf16 v[112:115], v[156:159], v[164:167], v[112:115]
	v_mfma_f32_16x16x32_bf16 v[100:103], v[148:151], v[172:175], v[100:103]
	v_mfma_f32_16x16x32_bf16 v[96:99], v[156:159], v[172:175], v[96:99]
	v_mfma_f32_16x16x32_bf16 v[84:87], v[148:151], v[212:215], v[84:87]
	v_mfma_f32_16x16x32_bf16 v[80:83], v[156:159], v[212:215], v[80:83]
	v_mfma_f32_16x16x32_bf16 v[68:71], v[148:151], v[220:223], v[68:71]
	v_mfma_f32_16x16x32_bf16 v[64:67], v[156:159], v[220:223], v[64:67]
	s_barrier
; #define PG8_STAGE(bufoff, gbase, voff) do { _Pragma("unroll") for (int _i = 0; _i < 2; ++_i) \
;         __builtin_amdgcn_global_load_lds((const unsigned*)((const char*)(gbase) + (voff)[_i]), (PG8_LAS unsigned*)(lds + (bufoff) + ldsw + _i * 8192), 16, 0, 0); } while (0)
; #define PG8_LDA(dst, b, h) do { _Pragma("unroll") for (int m = 0; m < 4; ++m) _Pragma("unroll") for (int k = 0; k < 2; ++k) dst[m][k] = *(const PG8_LAS bf16x8*)(lds + PG8_SA(b, h) + aoff + m * 2048 + k * 1024); } while (0)
; #define PG8_WAIT_V(n) asm volatile("s_waitcnt vmcnt(" #n ")" ::: "memory")
; template <class Epi, class Sched, bool ALIGN_EPI = false, bool SP2 = false>
; __device__ __forceinline__ void gemm_phase(PG8_LAS unsigned char* lds, const Gemm g, const Sched& S, const Epi& E) {
;     ...
;             PG8_LDA(At, 1, 1); PG8_STAGE(PG8_SB(1, 0), b3, voffB); PG8_STAGE(PG8_SB(1, 1), b3 + hstep, voffB); PG8_STAGE(PG8_SA(1, 0), a3, voffA);
;             PG8_WAIT_V(8); PG8_WAIT_L(0); PG8_BAR; PG8_MMA(1, 0, At, B0); PG8_MMA(1, 1, At, B1); PG8_BAR; PG8_SCHED;
;             } else {
;             PG8_LDB(B0, 0, 0); PG8_SCHED; PG8_LDA(At, 0, 0); PG8_STAGE(PG8_SA(1, 1), a1 + hstep, voffA);
;             PG8_WAIT_L(8); PG8_BAR; PG8_WAIT_L(0); PG8_MMA(0, 0, At, B0); PG8_BAR; PG8_SCHED;
;             PG8_LDB(B1, 0, 1); PG8_STAGE(PG8_SB(0, 0), b2, voffB);
;             PG8_BAR; PG8_WAIT_L(0); PG8_MMA(0, 1, At, B1); PG8_BAR;
;             PG8_LDA(At, 0, 1); PG8_STAGE(PG8_SA(0, 0), a2, voffA);
;             PG8_BAR; PG8_WAIT_L(0); PG8_MMA(1, 0, At, B0); PG8_BAR; PG8_SCHED;
;             PG8_STAGE(PG8_SB(0, 1), b2 + hstep, voffB);
;             PG8_WAIT_V(6); PG8_BAR; PG8_MMA(1, 1, At, B1); PG8_BAR;
;             PG8_LDB(B0, 1, 0); PG8_SCHED; PG8_LDA(At, 1, 0); PG8_STAGE(PG8_SA(0, 1), a2 + hstep, voffA);
;             PG8_WAIT_L(8); PG8_BAR; PG8_WAIT_L(0); PG8_MMA(0, 0, At, B0); PG8_BAR; PG8_SCHED;
;             PG8_LDB(B1, 1, 1); PG8_STAGE(PG8_SB(1, 0), b3, voffB);
;             PG8_BAR; PG8_WAIT_L(0); PG8_MMA(0, 1, At, B1); PG8_BAR;
;             PG8_LDA(At, 1, 1); PG8_STAGE(PG8_SA(1, 0), a3, voffA);
;             PG8_BAR; PG8_WAIT_L(0); PG8_MMA(1, 0, At, B0); PG8_BAR; PG8_SCHED;
;             PG8_STAGE(PG8_SB(1, 1), b3 + hstep, voffB);
;             PG8_WAIT_V(6); PG8_BAR; PG8_MMA(1, 1, At, B1); PG8_BAR;
;             }
;         }
;         if constexpr (ALIGN_EPI) { if (wr == 0) PG8_BAR; }
	s_add_i32 s58, s63, s2
	v_lshl_add_u64 v[178:179], v[178:179], 0, s[36:37]
	s_mov_b32 m0, s58
	ds_read_b128 v[160:163], v245 offset:49152
	ds_read_b128 v[164:167], v245 offset:50176
	ds_read_b128 v[168:171], v245 offset:51200
	ds_read_b128 v[172:175], v245 offset:52224
	ds_read_b128 v[208:211], v245 offset:53248
	ds_read_b128 v[212:215], v245 offset:54272
	ds_read_b128 v[216:219], v245 offset:55296
	ds_read_b128 v[220:223], v245 offset:56320
	global_load_lds_dwordx4 v[178:179], off
	s_add_i32 m0, s58, 0x2000
	s_add_u32 s56, s56, 0x40080
	v_lshl_add_u64 v[178:179], v[224:225], 0, s[36:37]
	s_addc_u32 s57, s57, 0
	s_add_i32 s58, s64, s2
	global_load_lds_dwordx4 v[178:179], off
	v_lshl_add_u64 v[178:179], s[56:57], 0, v[198:199]
	s_mov_b32 m0, s58
	s_nop 0
	global_load_lds_dwordx4 v[178:179], off
	v_lshl_add_u64 v[178:179], s[56:57], 0, v[194:195]
	s_add_i32 m0, s58, 0x2000
	s_nop 0
	global_load_lds_dwordx4 v[178:179], off
	v_lshl_add_u64 v[178:179], v[226:227], 0, s[36:37]
	s_mov_b32 m0, s24
	s_nop 0
	global_load_lds_dwordx4 v[178:179], off
	v_lshl_add_u64 v[178:179], v[228:229], 0, s[36:37]
	s_mov_b32 m0, s25
	s_nop 0
	global_load_lds_dwordx4 v[178:179], off
	s_waitcnt vmcnt(8)
	s_waitcnt lgkmcnt(0)
	s_barrier
	s_waitcnt lgkmcnt(0)
	v_mfma_f32_16x16x32_bf16 v[60:63], v[128:131], v[160:163], v[60:63]
	v_mfma_f32_16x16x32_bf16 v[56:59], v[136:139], v[160:163], v[56:59]
	v_mfma_f32_16x16x32_bf16 v[48:51], v[128:131], v[168:171], v[48:51]
	v_mfma_f32_16x16x32_bf16 v[40:43], v[136:139], v[168:171], v[40:43]
	v_mfma_f32_16x16x32_bf16 v[32:35], v[128:131], v[208:211], v[32:35]
	v_mfma_f32_16x16x32_bf16 v[24:27], v[136:139], v[208:211], v[24:27]
	v_mfma_f32_16x16x32_bf16 v[16:19], v[128:131], v[216:219], v[16:19]
	v_mfma_f32_16x16x32_bf16 v[8:11], v[136:139], v[216:219], v[8:11]
	v_mfma_f32_16x16x32_bf16 v[60:63], v[132:135], v[164:167], v[60:63]
	v_mfma_f32_16x16x32_bf16 v[56:59], v[140:143], v[164:167], v[56:59]
	v_mfma_f32_16x16x32_bf16 v[48:51], v[132:135], v[172:175], v[48:51]
	v_mfma_f32_16x16x32_bf16 v[40:43], v[140:143], v[172:175], v[40:43]
	v_mfma_f32_16x16x32_bf16 v[32:35], v[132:135], v[212:215], v[32:35]
	v_mfma_f32_16x16x32_bf16 v[24:27], v[140:143], v[212:215], v[24:27]
	v_mfma_f32_16x16x32_bf16 v[16:19], v[132:135], v[220:223], v[16:19]
	v_mfma_f32_16x16x32_bf16 v[8:11], v[140:143], v[220:223], v[8:11]
	v_mfma_f32_16x16x32_bf16 v[52:55], v[144:147], v[160:163], v[52:55]
	v_mfma_f32_16x16x32_bf16 v[44:47], v[152:155], v[160:163], v[44:47]
	v_mfma_f32_16x16x32_bf16 v[36:39], v[144:147], v[168:171], v[36:39]
	v_mfma_f32_16x16x32_bf16 v[28:31], v[152:155], v[168:171], v[28:31]
	v_mfma_f32_16x16x32_bf16 v[20:23], v[144:147], v[208:211], v[20:23]
	v_mfma_f32_16x16x32_bf16 v[12:15], v[152:155], v[208:211], v[12:15]
	v_mfma_f32_16x16x32_bf16 v[4:7], v[144:147], v[216:219], v[4:7]
	v_mfma_f32_16x16x32_bf16 v[0:3], v[152:155], v[216:219], v[0:3]
	v_mfma_f32_16x16x32_bf16 v[52:55], v[148:151], v[164:167], v[52:55]
	v_mfma_f32_16x16x32_bf16 v[44:47], v[156:159], v[164:167], v[44:47]
	v_mfma_f32_16x16x32_bf16 v[36:39], v[148:151], v[172:175], v[36:39]
	v_mfma_f32_16x16x32_bf16 v[28:31], v[156:159], v[172:175], v[28:31]
	v_mfma_f32_16x16x32_bf16 v[20:23], v[148:151], v[212:215], v[20:23]
	v_mfma_f32_16x16x32_bf16 v[12:15], v[156:159], v[212:215], v[12:15]
	v_mfma_f32_16x16x32_bf16 v[4:7], v[148:151], v[220:223], v[4:7]
	v_mfma_f32_16x16x32_bf16 v[0:3], v[156:159], v[220:223], v[0:3]
	s_barrier
	s_add_i32 s62, s62, 2
	s_add_u32 s49, s49, 0x100
	s_addc_u32 s51, s51, 0
	s_add_u32 s4, s4, 0x100
	s_addc_u32 s5, s5, 0
	s_cmp_gt_u32 s62, 13
	s_cbranch_scc0 .LBB0_143
	s_and_b64 vcc, exec, s[44:45]
	s_cbranch_vccz .LBB0_146
	s_barrier

; #define PG8_STAGE(bufoff, gbase, voff) do { _Pragma("unroll") for (int _i = 0; _i < 2; ++_i) \
;         __builtin_amdgcn_global_load_lds((const unsigned*)((const char*)(gbase) + (voff)[_i]), (PG8_LAS unsigned*)(lds + (bufoff) + ldsw + _i * 8192), 16, 0, 0); } while (0)
; #define PG8_LDA(dst, b, h) do { _Pragma("unroll") for (int m = 0; m < 4; ++m) _Pragma("unroll") for (int k = 0; k < 2; ++k) dst[m][k] = *(const PG8_LAS bf16x8*)(lds + PG8_SA(b, h) + aoff + m * 2048 + k * 1024); } while (0)
; #define PG8_LDB(dst, b, h) do { _Pragma("unroll") for (int n = 0; n < 2; ++n) _Pragma("unroll") for (int k = 0; k < 2; ++k) dst[n][k] = *(const PG8_LAS bf16x8*)(lds + PG8_SB(b, h) + boff + n * 2048 + k * 1024); } while (0)
; #define PG8_MMA(ai, bj, At, Bt) do { __builtin_amdgcn_s_setprio(1); _Pragma("unroll") for (int m = 0; m < 4; ++m) _Pragma("unroll") for (int n = 0; n < 2; ++n) _Pragma("unroll") for (int k = 0; k < 2; ++k) \
;         acc[ai][bj][m][n] = __builtin_amdgcn_mfma_f32_16x16x32_bf16(Bt[n][k], At[m][k], acc[ai][bj][m][n], 0, 0, 0); __builtin_amdgcn_s_setprio(0); } while (0)
; #define PG8_WAIT_V(n) asm volatile("s_waitcnt vmcnt(" #n ")" ::: "memory")
; #define PG8_WAIT_L(n) asm volatile("s_waitcnt lgkmcnt(" #n ")" ::: "memory")
; #define PG8_BAR __builtin_amdgcn_s_barrier()
; #define PG8_SCHED __builtin_amdgcn_sched_barrier(0)
; template <class Epi, class Sched, bool ALIGN_EPI = false, bool SP2 = false>
; __device__ __forceinline__ void gemm_phase(PG8_LAS unsigned char* lds, const Gemm g, const Sched& S, const Epi& E) {
;     ...
;             PG8_LDB(B0, 0, 0); PG8_LDB(B1, 0, 1); PG8_SCHED; PG8_LDA(At, 0, 0); PG8_STAGE(PG8_SA(1, 1), a1 + hstep, voffA);
;             PG8_WAIT_V(8); PG8_WAIT_L(0); PG8_BAR; PG8_MMA(0, 0, At, B0); PG8_MMA(0, 1, At, B1); PG8_BAR; PG8_SCHED;
;             PG8_LDA(At, 0, 1); PG8_STAGE(PG8_SB(0, 0), b2, voffB); PG8_STAGE(PG8_SB(0, 1), b2 + hstep, voffB); PG8_STAGE(PG8_SA(0, 0), a2, voffA);
;             PG8_WAIT_V(8); PG8_WAIT_L(0); PG8_BAR; PG8_MMA(1, 0, At, B0); PG8_MMA(1, 1, At, B1); PG8_BAR; PG8_SCHED;
.LBB0_265:
	s_add_u32 s16, s0, 0xfffc0080
	s_addc_u32 s17, s1, -1
	s_add_i32 s25, 0, 0x10000
	s_cmp_eq_u32 s24, 12
	s_cselect_b32 s27, s11, s17
	s_cselect_b32 s26, s14, s16
	v_add_u32_e32 v146, s25, v149
	s_cselect_b32 s17, s20, s23
	s_cselect_b32 s16, s21, s22
	s_add_i32 s30, 0, 0x14000
	ds_read_b128 v[142:145], v146
	ds_read_b128 v[154:157], v146 offset:1024
	ds_read_b128 v[158:161], v146 offset:2048
	ds_read_b128 v[162:165], v146 offset:3072
	v_add_u32_e32 v146, s30, v149
	ds_read_b128 v[166:169], v146
	ds_read_b128 v[170:173], v146 offset:1024
	ds_read_b128 v[194:197], v146 offset:2048
	ds_read_b128 v[198:201], v146 offset:3072
	v_lshl_add_u64 v[146:147], s[0:1], 0, v[140:141]
	s_add_i32 m0, s54, 0xc000
	ds_read_b128 v[202:205], v153
	ds_read_b128 v[206:209], v153 offset:1024
	ds_read_b128 v[210:213], v153 offset:2048
	ds_read_b128 v[214:217], v153 offset:3072
	ds_read_b128 v[218:221], v153 offset:4096
	ds_read_b128 v[222:225], v153 offset:5120
	ds_read_b128 v[226:229], v153 offset:6144
	ds_read_b128 v[230:233], v153 offset:7168
	global_load_lds_dwordx4 v[146:147], off
	v_lshl_add_u64 v[146:147], s[0:1], 0, v[138:139]
	s_add_i32 m0, s54, 0xe000
	s_nop 0
	global_load_lds_dwordx4 v[146:147], off
	s_waitcnt vmcnt(8)
	s_waitcnt lgkmcnt(0)
	s_barrier
	s_waitcnt lgkmcnt(0)
	v_mfma_f32_16x16x32_bf16 v[124:127], v[142:145], v[202:205], v[124:127]
	v_mfma_f32_16x16x32_bf16 v[120:123], v[158:161], v[202:205], v[120:123]
	v_mfma_f32_16x16x32_bf16 v[108:111], v[142:145], v[210:213], v[108:111]
	v_mfma_f32_16x16x32_bf16 v[104:107], v[158:161], v[210:213], v[104:107]
	v_mfma_f32_16x16x32_bf16 v[92:95], v[142:145], v[218:221], v[92:95]
	v_mfma_f32_16x16x32_bf16 v[88:91], v[158:161], v[218:221], v[88:91]
	v_mfma_f32_16x16x32_bf16 v[76:79], v[142:145], v[226:229], v[76:79]
	v_mfma_f32_16x16x32_bf16 v[72:75], v[158:161], v[226:229], v[72:75]
	v_mfma_f32_16x16x32_bf16 v[124:127], v[154:157], v[206:209], v[124:127]
	v_mfma_f32_16x16x32_bf16 v[120:123], v[162:165], v[206:209], v[120:123]
	v_mfma_f32_16x16x32_bf16 v[108:111], v[154:157], v[214:217], v[108:111]
	v_mfma_f32_16x16x32_bf16 v[104:107], v[162:165], v[214:217], v[104:107]
	v_mfma_f32_16x16x32_bf16 v[92:95], v[154:157], v[222:225], v[92:95]
	v_mfma_f32_16x16x32_bf16 v[88:91], v[162:165], v[222:225], v[88:91]
	v_mfma_f32_16x16x32_bf16 v[76:79], v[154:157], v[230:233], v[76:79]
	v_mfma_f32_16x16x32_bf16 v[72:75], v[162:165], v[230:233], v[72:75]
	v_mfma_f32_16x16x32_bf16 v[116:119], v[166:169], v[202:205], v[116:119]
	v_mfma_f32_16x16x32_bf16 v[112:115], v[194:197], v[202:205], v[112:115]
	v_mfma_f32_16x16x32_bf16 v[100:103], v[166:169], v[210:213], v[100:103]
	v_mfma_f32_16x16x32_bf16 v[96:99], v[194:197], v[210:213], v[96:99]
	v_mfma_f32_16x16x32_bf16 v[84:87], v[166:169], v[218:221], v[84:87]
	v_mfma_f32_16x16x32_bf16 v[80:83], v[194:197], v[218:221], v[80:83]
	v_mfma_f32_16x16x32_bf16 v[68:71], v[166:169], v[226:229], v[68:71]
	v_mfma_f32_16x16x32_bf16 v[64:67], v[194:197], v[226:229], v[64:67]
	v_mfma_f32_16x16x32_bf16 v[116:119], v[170:173], v[206:209], v[116:119]
	v_mfma_f32_16x16x32_bf16 v[112:115], v[198:201], v[206:209], v[112:115]
	v_mfma_f32_16x16x32_bf16 v[100:103], v[170:173], v[214:217], v[100:103]
	v_mfma_f32_16x16x32_bf16 v[96:99], v[198:201], v[214:217], v[96:99]
	v_mfma_f32_16x16x32_bf16 v[84:87], v[170:173], v[222:225], v[84:87]
	v_mfma_f32_16x16x32_bf16 v[80:83], v[198:201], v[222:225], v[80:83]
	v_mfma_f32_16x16x32_bf16 v[68:71], v[170:173], v[230:233], v[68:71]
	v_mfma_f32_16x16x32_bf16 v[64:67], v[198:201], v[230:233], v[64:67]
	s_barrier
	s_add_i32 s25, s25, s2
	v_lshl_add_u64 v[146:147], s[16:17], 0, v[132:133]
	s_mov_b32 m0, s25
	ds_read_b128 v[202:205], v153 offset:16384
	ds_read_b128 v[206:209], v153 offset:17408
	ds_read_b128 v[210:213], v153 offset:18432
	ds_read_b128 v[214:217], v153 offset:19456
	ds_read_b128 v[218:221], v153 offset:20480
	ds_read_b128 v[222:225], v153 offset:21504
	ds_read_b128 v[226:229], v153 offset:22528
	ds_read_b128 v[230:233], v153 offset:23552
	global_load_lds_dwordx4 v[146:147], off
	s_add_i32 m0, s25, 0x2000
	s_add_u32 s28, s16, 0x40000
	v_lshl_add_u64 v[174:175], s[16:17], 0, v[128:129]
	s_addc_u32 s29, s17, 0
	s_add_i32 s25, s30, s2
	global_load_lds_dwordx4 v[174:175], off
	v_lshl_add_u64 v[178:179], s[28:29], 0, v[132:133]
	s_mov_b32 m0, s25
	v_lshl_add_u64 v[234:235], s[26:27], 0, v[130:131]
	global_load_lds_dwordx4 v[178:179], off
	v_lshl_add_u64 v[178:179], s[28:29], 0, v[128:129]
	s_add_i32 m0, s25, 0x2000
	s_nop 0
	global_load_lds_dwordx4 v[178:179], off
	v_lshl_add_u64 v[178:179], s[26:27], 0, v[134:135]
	s_mov_b32 m0, s54
	s_nop 0
	global_load_lds_dwordx4 v[178:179], off
	s_mov_b32 m0, s55
	s_nop 0
	global_load_lds_dwordx4 v[234:235], off
	s_waitcnt vmcnt(8)
	s_waitcnt lgkmcnt(0)
	s_barrier
; #define PG8_STAGE(bufoff, gbase, voff) do { _Pragma("unroll") for (int _i = 0; _i < 2; ++_i) \
;         __builtin_amdgcn_global_load_lds((const unsigned*)((const char*)(gbase) + (voff)[_i]), (PG8_LAS unsigned*)(lds + (bufoff) + ldsw + _i * 8192), 16, 0, 0); } while (0)
; #define PG8_LDA(dst, b, h) do { _Pragma("unroll") for (int m = 0; m < 4; ++m) _Pragma("unroll") for (int k = 0; k < 2; ++k) dst[m][k] = *(const PG8_LAS bf16x8*)(lds + PG8_SA(b, h) + aoff + m * 2048 + k * 1024); } while (0)
; #define PG8_LDB(dst, b, h) do { _Pragma("unroll") for (int n = 0; n < 2; ++n) _Pragma("unroll") for (int k = 0; k < 2; ++k) dst[n][k] = *(const PG8_LAS bf16x8*)(lds + PG8_SB(b, h) + boff + n * 2048 + k * 1024); } while (0)
; #define PG8_MMA(ai, bj, At, Bt) do { __builtin_amdgcn_s_setprio(1); _Pragma("unroll") for (int m = 0; m < 4; ++m) _Pragma("unroll") for (int n = 0; n < 2; ++n) _Pragma("unroll") for (int k = 0; k < 2; ++k) \
;         acc[ai][bj][m][n] = __builtin_amdgcn_mfma_f32_16x16x32_bf16(Bt[n][k], At[m][k], acc[ai][bj][m][n], 0, 0, 0); __builtin_amdgcn_s_setprio(0); } while (0)
; #define PG8_WAIT_V(n) asm volatile("s_waitcnt vmcnt(" #n ")" ::: "memory")
; #define PG8_WAIT_L(n) asm volatile("s_waitcnt lgkmcnt(" #n ")" ::: "memory")
; #define PG8_BAR __builtin_amdgcn_s_barrier()
; #define PG8_SCHED __builtin_amdgcn_sched_barrier(0)
; template <class Epi, class Sched, bool ALIGN_EPI = false, bool SP2 = false>
; __device__ __forceinline__ void gemm_phase(PG8_LAS unsigned char* lds, const Gemm g, const Sched& S, const Epi& E) {
;     ...
;             PG8_WAIT_V(8); PG8_WAIT_L(0); PG8_BAR; PG8_MMA(1, 0, At, B0); PG8_MMA(1, 1, At, B1); PG8_BAR; PG8_SCHED;
;             PG8_LDB(B0, 1, 0); PG8_LDB(B1, 1, 1); PG8_SCHED; PG8_LDA(At, 1, 0); PG8_STAGE(PG8_SA(0, 1), a2 + hstep, voffA);
;             PG8_WAIT_V(8); PG8_WAIT_L(0); PG8_BAR; PG8_MMA(0, 0, At, B0); PG8_MMA(0, 1, At, B1); PG8_BAR; PG8_SCHED;
;             PG8_LDA(At, 1, 1); PG8_STAGE(PG8_SB(1, 0), b3, voffB); PG8_STAGE(PG8_SB(1, 1), b3 + hstep, voffB); PG8_STAGE(PG8_SA(1, 0), a3, voffA);
	s_waitcnt lgkmcnt(0)
	v_mfma_f32_16x16x32_bf16 v[60:63], v[142:145], v[202:205], v[60:63]
	v_mfma_f32_16x16x32_bf16 v[56:59], v[158:161], v[202:205], v[56:59]
	v_mfma_f32_16x16x32_bf16 v[44:47], v[142:145], v[210:213], v[44:47]
	v_mfma_f32_16x16x32_bf16 v[40:43], v[158:161], v[210:213], v[40:43]
	v_mfma_f32_16x16x32_bf16 v[28:31], v[142:145], v[218:221], v[28:31]
	v_mfma_f32_16x16x32_bf16 v[24:27], v[158:161], v[218:221], v[24:27]
	v_mfma_f32_16x16x32_bf16 v[12:15], v[142:145], v[226:229], v[12:15]
	v_mfma_f32_16x16x32_bf16 v[8:11], v[158:161], v[226:229], v[8:11]
	v_mfma_f32_16x16x32_bf16 v[60:63], v[154:157], v[206:209], v[60:63]
	v_mfma_f32_16x16x32_bf16 v[56:59], v[162:165], v[206:209], v[56:59]
	v_mfma_f32_16x16x32_bf16 v[44:47], v[154:157], v[214:217], v[44:47]
	v_mfma_f32_16x16x32_bf16 v[40:43], v[162:165], v[214:217], v[40:43]
	v_mfma_f32_16x16x32_bf16 v[28:31], v[154:157], v[222:225], v[28:31]
	v_mfma_f32_16x16x32_bf16 v[24:27], v[162:165], v[222:225], v[24:27]
	v_mfma_f32_16x16x32_bf16 v[12:15], v[154:157], v[230:233], v[12:15]
	v_mfma_f32_16x16x32_bf16 v[8:11], v[162:165], v[230:233], v[8:11]
	v_mfma_f32_16x16x32_bf16 v[52:55], v[166:169], v[202:205], v[52:55]
	v_mfma_f32_16x16x32_bf16 v[48:51], v[194:197], v[202:205], v[48:51]
	v_mfma_f32_16x16x32_bf16 v[36:39], v[166:169], v[210:213], v[36:39]
	v_mfma_f32_16x16x32_bf16 v[32:35], v[194:197], v[210:213], v[32:35]
	v_mfma_f32_16x16x32_bf16 v[20:23], v[166:169], v[218:221], v[20:23]
	v_mfma_f32_16x16x32_bf16 v[16:19], v[194:197], v[218:221], v[16:19]
	v_mfma_f32_16x16x32_bf16 v[4:7], v[166:169], v[226:229], v[4:7]
	v_mfma_f32_16x16x32_bf16 v[0:3], v[194:197], v[226:229], v[0:3]
	v_mfma_f32_16x16x32_bf16 v[52:55], v[170:173], v[206:209], v[52:55]
	v_mfma_f32_16x16x32_bf16 v[48:51], v[198:201], v[206:209], v[48:51]
	v_mfma_f32_16x16x32_bf16 v[36:39], v[170:173], v[214:217], v[36:39]
	v_mfma_f32_16x16x32_bf16 v[32:35], v[198:201], v[214:217], v[32:35]
	v_mfma_f32_16x16x32_bf16 v[20:23], v[170:173], v[222:225], v[20:23]
	v_mfma_f32_16x16x32_bf16 v[16:19], v[198:201], v[222:225], v[16:19]
	v_mfma_f32_16x16x32_bf16 v[4:7], v[170:173], v[230:233], v[4:7]
	v_mfma_f32_16x16x32_bf16 v[0:3], v[198:201], v[230:233], v[0:3]
	s_barrier
	s_add_i32 s25, 0, 0x18000
	v_add_u32_e32 v148, s25, v149
	s_add_i32 s28, 0, 0x1c000
	ds_read_b128 v[142:145], v148
	ds_read_b128 v[154:157], v148 offset:1024
	ds_read_b128 v[158:161], v148 offset:2048
	ds_read_b128 v[162:165], v148 offset:3072
	v_add_u32_e32 v148, s28, v149
	ds_read_b128 v[166:169], v148
	ds_read_b128 v[170:173], v148 offset:1024
	ds_read_b128 v[194:197], v148 offset:2048
	ds_read_b128 v[198:201], v148 offset:3072
	s_add_u32 s26, s26, 0x40000
	s_addc_u32 s27, s27, 0
	s_mov_b32 m0, s56
	v_lshl_add_u64 v[236:237], s[26:27], 0, v[134:135]
	ds_read_b128 v[202:205], v153 offset:32768
	ds_read_b128 v[206:209], v153 offset:33792
	ds_read_b128 v[210:213], v153 offset:34816
	ds_read_b128 v[214:217], v153 offset:35840
	ds_read_b128 v[218:221], v153 offset:36864
	ds_read_b128 v[222:225], v153 offset:37888
	ds_read_b128 v[226:229], v153 offset:38912
	ds_read_b128 v[230:233], v153 offset:39936
	global_load_lds_dwordx4 v[236:237], off
	v_lshl_add_u64 v[236:237], s[26:27], 0, v[130:131]
	s_mov_b32 m0, s57
	s_nop 0
	global_load_lds_dwordx4 v[236:237], off
	s_waitcnt vmcnt(8)
	s_waitcnt lgkmcnt(0)
	s_barrier
	s_waitcnt lgkmcnt(0)
	v_mfma_f32_16x16x32_bf16 v[124:127], v[142:145], v[202:205], v[124:127]
	v_mfma_f32_16x16x32_bf16 v[120:123], v[158:161], v[202:205], v[120:123]
	v_mfma_f32_16x16x32_bf16 v[108:111], v[142:145], v[210:213], v[108:111]
	v_mfma_f32_16x16x32_bf16 v[104:107], v[158:161], v[210:213], v[104:107]
	v_mfma_f32_16x16x32_bf16 v[92:95], v[142:145], v[218:221], v[92:95]
	v_mfma_f32_16x16x32_bf16 v[88:91], v[158:161], v[218:221], v[88:91]
	v_mfma_f32_16x16x32_bf16 v[76:79], v[142:145], v[226:229], v[76:79]
	v_mfma_f32_16x16x32_bf16 v[72:75], v[158:161], v[226:229], v[72:75]
	v_mfma_f32_16x16x32_bf16 v[124:127], v[154:157], v[206:209], v[124:127]
	v_mfma_f32_16x16x32_bf16 v[120:123], v[162:165], v[206:209], v[120:123]
	v_mfma_f32_16x16x32_bf16 v[108:111], v[154:157], v[214:217], v[108:111]
	v_mfma_f32_16x16x32_bf16 v[104:107], v[162:165], v[214:217], v[104:107]
	v_mfma_f32_16x16x32_bf16 v[92:95], v[154:157], v[222:225], v[92:95]
	v_mfma_f32_16x16x32_bf16 v[88:91], v[162:165], v[222:225], v[88:91]
	v_mfma_f32_16x16x32_bf16 v[76:79], v[154:157], v[230:233], v[76:79]
	v_mfma_f32_16x16x32_bf16 v[72:75], v[162:165], v[230:233], v[72:75]
	v_mfma_f32_16x16x32_bf16 v[116:119], v[166:169], v[202:205], v[116:119]
	v_mfma_f32_16x16x32_bf16 v[112:115], v[194:197], v[202:205], v[112:115]
	v_mfma_f32_16x16x32_bf16 v[100:103], v[166:169], v[210:213], v[100:103]
	v_mfma_f32_16x16x32_bf16 v[96:99], v[194:197], v[210:213], v[96:99]
	v_mfma_f32_16x16x32_bf16 v[84:87], v[166:169], v[218:221], v[84:87]
	v_mfma_f32_16x16x32_bf16 v[80:83], v[194:197], v[218:221], v[80:83]
	v_mfma_f32_16x16x32_bf16 v[68:71], v[166:169], v[226:229], v[68:71]
	v_mfma_f32_16x16x32_bf16 v[64:67], v[194:197], v[226:229], v[64:67]
	v_mfma_f32_16x16x32_bf16 v[116:119], v[170:173], v[206:209], v[116:119]
	v_mfma_f32_16x16x32_bf16 v[112:115], v[198:201], v[206:209], v[112:115]
	v_mfma_f32_16x16x32_bf16 v[100:103], v[170:173], v[214:217], v[100:103]
	v_mfma_f32_16x16x32_bf16 v[96:99], v[198:201], v[214:217], v[96:99]
	v_mfma_f32_16x16x32_bf16 v[84:87], v[170:173], v[222:225], v[84:87]
	v_mfma_f32_16x16x32_bf16 v[80:83], v[198:201], v[222:225], v[80:83]
	v_mfma_f32_16x16x32_bf16 v[68:71], v[170:173], v[230:233], v[68:71]
	v_mfma_f32_16x16x32_bf16 v[64:67], v[198:201], v[230:233], v[64:67]
	s_barrier
; #define PG8_STAGE(bufoff, gbase, voff) do { _Pragma("unroll") for (int _i = 0; _i < 2; ++_i) \
;         __builtin_amdgcn_global_load_lds((const unsigned*)((const char*)(gbase) + (voff)[_i]), (PG8_LAS unsigned*)(lds + (bufoff) + ldsw + _i * 8192), 16, 0, 0); } while (0)
; #define PG8_LDA(dst, b, h) do { _Pragma("unroll") for (int m = 0; m < 4; ++m) _Pragma("unroll") for (int k = 0; k < 2; ++k) dst[m][k] = *(const PG8_LAS bf16x8*)(lds + PG8_SA(b, h) + aoff + m * 2048 + k * 1024); } while (0)
; #define PG8_MMA(ai, bj, At, Bt) do { __builtin_amdgcn_s_setprio(1); _Pragma("unroll") for (int m = 0; m < 4; ++m) _Pragma("unroll") for (int n = 0; n < 2; ++n) _Pragma("unroll") for (int k = 0; k < 2; ++k) \
;         acc[ai][bj][m][n] = __builtin_amdgcn_mfma_f32_16x16x32_bf16(Bt[n][k], At[m][k], acc[ai][bj][m][n], 0, 0, 0); __builtin_amdgcn_s_setprio(0); } while (0)
; #define PG8_WAIT_V(n) asm volatile("s_waitcnt vmcnt(" #n ")" ::: "memory")
; #define PG8_WAIT_L(n) asm volatile("s_waitcnt lgkmcnt(" #n ")" ::: "memory")
; #define PG8_BAR __builtin_amdgcn_s_barrier()
; #define PG8_SCHED __builtin_amdgcn_sched_barrier(0)
; template <class Epi, class Sched, bool ALIGN_EPI = false, bool SP2 = false>
; __device__ __forceinline__ void gemm_phase(PG8_LAS unsigned char* lds, const Gemm g, const Sched& S, const Epi& E) {
;     ...
;             PG8_LDA(At, 1, 1); PG8_STAGE(PG8_SB(1, 0), b3, voffB); PG8_STAGE(PG8_SB(1, 1), b3 + hstep, voffB); PG8_STAGE(PG8_SA(1, 0), a3, voffA);
;             PG8_WAIT_V(8); PG8_WAIT_L(0); PG8_BAR; PG8_MMA(1, 0, At, B0); PG8_MMA(1, 1, At, B1); PG8_BAR; PG8_SCHED;
;     ...
;         if constexpr (ALIGN_EPI) { if (wr == 0) PG8_BAR; }
	s_add_i32 s25, s25, s2
	v_lshl_add_u64 v[146:147], v[146:147], 0, s[36:37]
	s_mov_b32 m0, s25
	ds_read_b128 v[202:205], v153 offset:49152
	ds_read_b128 v[206:209], v153 offset:50176
	ds_read_b128 v[210:213], v153 offset:51200
	ds_read_b128 v[214:217], v153 offset:52224
	ds_read_b128 v[218:221], v153 offset:53248
	ds_read_b128 v[222:225], v153 offset:54272
	ds_read_b128 v[226:229], v153 offset:55296
	ds_read_b128 v[230:233], v153 offset:56320
	global_load_lds_dwordx4 v[146:147], off
	s_add_i32 m0, s25, 0x2000
	s_add_u32 s16, s16, 0x40080
	v_lshl_add_u64 v[146:147], v[174:175], 0, s[36:37]
	s_addc_u32 s17, s17, 0
	s_add_i32 s25, s28, s2
	global_load_lds_dwordx4 v[146:147], off
	v_lshl_add_u64 v[146:147], s[16:17], 0, v[132:133]
	s_mov_b32 m0, s25
	s_nop 0
	global_load_lds_dwordx4 v[146:147], off
	v_lshl_add_u64 v[146:147], s[16:17], 0, v[128:129]
	s_add_i32 m0, s25, 0x2000
	s_nop 0
	global_load_lds_dwordx4 v[146:147], off
	v_lshl_add_u64 v[146:147], v[178:179], 0, s[36:37]
	s_mov_b32 m0, s59
	s_nop 0
	global_load_lds_dwordx4 v[146:147], off
	v_lshl_add_u64 v[146:147], v[234:235], 0, s[36:37]
	s_mov_b32 m0, s62
	s_nop 0
	global_load_lds_dwordx4 v[146:147], off
	s_waitcnt vmcnt(8)
	s_waitcnt lgkmcnt(0)
	s_barrier
	s_waitcnt lgkmcnt(0)
	v_mfma_f32_16x16x32_bf16 v[60:63], v[142:145], v[202:205], v[60:63]
	v_mfma_f32_16x16x32_bf16 v[56:59], v[158:161], v[202:205], v[56:59]
	v_mfma_f32_16x16x32_bf16 v[44:47], v[142:145], v[210:213], v[44:47]
	v_mfma_f32_16x16x32_bf16 v[40:43], v[158:161], v[210:213], v[40:43]
	v_mfma_f32_16x16x32_bf16 v[28:31], v[142:145], v[218:221], v[28:31]
	v_mfma_f32_16x16x32_bf16 v[24:27], v[158:161], v[218:221], v[24:27]
	v_mfma_f32_16x16x32_bf16 v[12:15], v[142:145], v[226:229], v[12:15]
	v_mfma_f32_16x16x32_bf16 v[8:11], v[158:161], v[226:229], v[8:11]
	v_mfma_f32_16x16x32_bf16 v[60:63], v[154:157], v[206:209], v[60:63]
	v_mfma_f32_16x16x32_bf16 v[56:59], v[162:165], v[206:209], v[56:59]
	v_mfma_f32_16x16x32_bf16 v[44:47], v[154:157], v[214:217], v[44:47]
	v_mfma_f32_16x16x32_bf16 v[40:43], v[162:165], v[214:217], v[40:43]
	v_mfma_f32_16x16x32_bf16 v[28:31], v[154:157], v[222:225], v[28:31]
	v_mfma_f32_16x16x32_bf16 v[24:27], v[162:165], v[222:225], v[24:27]
	v_mfma_f32_16x16x32_bf16 v[12:15], v[154:157], v[230:233], v[12:15]
	v_mfma_f32_16x16x32_bf16 v[8:11], v[162:165], v[230:233], v[8:11]
	v_mfma_f32_16x16x32_bf16 v[52:55], v[166:169], v[202:205], v[52:55]
	v_mfma_f32_16x16x32_bf16 v[48:51], v[194:197], v[202:205], v[48:51]
	v_mfma_f32_16x16x32_bf16 v[36:39], v[166:169], v[210:213], v[36:39]
	v_mfma_f32_16x16x32_bf16 v[32:35], v[194:197], v[210:213], v[32:35]
	v_mfma_f32_16x16x32_bf16 v[20:23], v[166:169], v[218:221], v[20:23]
	v_mfma_f32_16x16x32_bf16 v[16:19], v[194:197], v[218:221], v[16:19]
	v_mfma_f32_16x16x32_bf16 v[4:7], v[166:169], v[226:229], v[4:7]
	v_mfma_f32_16x16x32_bf16 v[0:3], v[194:197], v[226:229], v[0:3]
	v_mfma_f32_16x16x32_bf16 v[52:55], v[170:173], v[206:209], v[52:55]
	v_mfma_f32_16x16x32_bf16 v[48:51], v[198:201], v[206:209], v[48:51]
	v_mfma_f32_16x16x32_bf16 v[36:39], v[170:173], v[214:217], v[36:39]
	v_mfma_f32_16x16x32_bf16 v[32:35], v[198:201], v[214:217], v[32:35]
	v_mfma_f32_16x16x32_bf16 v[20:23], v[170:173], v[222:225], v[20:23]
	v_mfma_f32_16x16x32_bf16 v[16:19], v[198:201], v[222:225], v[16:19]
	v_mfma_f32_16x16x32_bf16 v[4:7], v[170:173], v[230:233], v[4:7]
	v_mfma_f32_16x16x32_bf16 v[0:3], v[198:201], v[230:233], v[0:3]
	s_barrier
	s_add_i32 s24, s24, 2
	s_add_u32 s22, s22, 0x100
	s_addc_u32 s23, s23, 0
	s_add_u32 s0, s0, 0x100
	s_addc_u32 s1, s1, 0
	s_cmp_gt_u32 s24, 13
	s_cbranch_scc0 .LBB0_265
	s_and_b64 vcc, exec, s[44:45]
	s_cbranch_vccz .LBB0_268
	s_barrier

; #define PG8_STAGE(bufoff, gbase, voff) do { _Pragma("unroll") for (int _i = 0; _i < 2; ++_i) \
;         __builtin_amdgcn_global_load_lds((const unsigned*)((const char*)(gbase) + (voff)[_i]), (PG8_LAS unsigned*)(lds + (bufoff) + ldsw + _i * 8192), 16, 0, 0); } while (0)
; #define PG8_LDA(dst, b, h) do { _Pragma("unroll") for (int m = 0; m < 4; ++m) _Pragma("unroll") for (int k = 0; k < 2; ++k) dst[m][k] = *(const PG8_LAS bf16x8*)(lds + PG8_SA(b, h) + aoff + m * 2048 + k * 1024); } while (0)
; #define PG8_LDB(dst, b, h) do { _Pragma("unroll") for (int n = 0; n < 2; ++n) _Pragma("unroll") for (int k = 0; k < 2; ++k) dst[n][k] = *(const PG8_LAS bf16x8*)(lds + PG8_SB(b, h) + boff + n * 2048 + k * 1024); } while (0)
; #define PG8_WAIT_V(n) asm volatile("s_waitcnt vmcnt(" #n ")" ::: "memory")
; #define PG8_WAIT_L(n) asm volatile("s_waitcnt lgkmcnt(" #n ")" ::: "memory")
; #define PG8_BAR __builtin_amdgcn_s_barrier()
; #define PG8_SCHED __builtin_amdgcn_sched_barrier(0)
; template <class Epi, class Sched, bool ALIGN_EPI = false, bool SP2 = false>
; __device__ __forceinline__ void gemm_phase(PG8_LAS unsigned char* lds, const Gemm g, const Sched& S, const Epi& E) {
;     ...
;         const bool has_next = S.next(ui + 1, nxt);
;         const char* nA = has_next ? (const char*)g.A + (size_t)nxt.pm * tstep : cA; const char* nB = has_next ? (const char*)g.Bt + (size_t)nxt.pn * tstep : cB;
;         for (int t = 0; t < nt; t += 2) {
;             const bool last = (t == nt - 2);
;             const char* a1 = cA + (size_t)(t + 1) * kstep;
;             const char* a2 = last ? nA : cA + (size_t)(t + 2) * kstep; const char* b2 = last ? nB : cB + (size_t)(t + 2) * kstep;
;             const char* a3 = a2 + kstep; const char* b3 = b2 + kstep;
;             if (last && has_next) S.a_ready(nxt);
;             if constexpr (SP2) {
;             PG8_LDB(B0, 0, 0); PG8_LDB(B1, 0, 1); PG8_SCHED; PG8_LDA(At, 0, 0); PG8_STAGE(PG8_SA(1, 1), a1 + hstep, voffA);
;             PG8_WAIT_V(8); PG8_WAIT_L(0); PG8_BAR; PG8_MMA(0, 0, At, B0); PG8_MMA(0, 1, At, B1); PG8_BAR; PG8_SCHED;
;             PG8_LDA(At, 0, 1); PG8_STAGE(PG8_SB(0, 0), b2, voffB); PG8_STAGE(PG8_SB(0, 1), b2 + hstep, voffB); PG8_STAGE(PG8_SA(0, 0), a2, voffA);
;             PG8_WAIT_V(8); PG8_WAIT_L(0); PG8_BAR; PG8_MMA(1, 0, At, B0); PG8_MMA(1, 1, At, B1); PG8_BAR; PG8_SCHED;
.LBB0_558:
	s_add_u32 s50, s48, 0xfffc0080
	s_addc_u32 s51, s49, -1
	s_add_i32 s56, 0, 0x10000
	s_cmp_eq_u32 s55, 12
	s_cselect_b32 s53, s33, s51
	s_cselect_b32 s52, s34, s50
	s_cselect_b32 s51, s35, s54
	s_cselect_b32 s50, s41, s43
	s_add_i32 s58, 0, 0x14000
	v_add_u32_e32 v124, s56, v201
	v_add_u32_e32 v168, s58, v201
	ds_read_b128 v[112:115], v124
	ds_read_b128 v[116:119], v124 offset:1024
	ds_read_b128 v[120:123], v124 offset:2048
	ds_read_b128 v[124:127], v124 offset:3072
	ds_read_b128 v[128:131], v168
	ds_read_b128 v[132:135], v168 offset:1024
	ds_read_b128 v[164:167], v168 offset:2048
	ds_read_b128 v[168:171], v168 offset:3072
	v_lshl_add_u64 v[178:179], s[48:49], 0, v[162:163]
	s_add_i32 m0, s21, 0xc000
	ds_read_b128 v[172:175], v203
	ds_read_b128 v[194:197], v203 offset:1024
	ds_read_b128 v[204:207], v203 offset:2048
	ds_read_b128 v[208:211], v203 offset:3072
	ds_read_b128 v[212:215], v203 offset:4096
	ds_read_b128 v[216:219], v203 offset:5120
	ds_read_b128 v[220:223], v203 offset:6144
	ds_read_b128 v[224:227], v203 offset:7168
	global_load_lds_dwordx4 v[178:179], off
	v_lshl_add_u64 v[178:179], s[48:49], 0, v[160:161]
	s_add_i32 m0, s21, 0xe000
	s_nop 0
	global_load_lds_dwordx4 v[178:179], off
	s_waitcnt vmcnt(8)
	s_waitcnt lgkmcnt(0)
	s_barrier
	s_waitcnt lgkmcnt(0)
	v_mfma_f32_16x16x32_bf16 v[148:151], v[112:115], v[172:175], v[148:151]
	v_mfma_f32_16x16x32_bf16 v[144:147], v[120:123], v[172:175], v[144:147]
	v_mfma_f32_16x16x32_bf16 v[108:111], v[112:115], v[204:207], v[108:111]
	v_mfma_f32_16x16x32_bf16 v[104:107], v[120:123], v[204:207], v[104:107]
	v_mfma_f32_16x16x32_bf16 v[92:95], v[112:115], v[212:215], v[92:95]
	v_mfma_f32_16x16x32_bf16 v[88:91], v[120:123], v[212:215], v[88:91]
	v_mfma_f32_16x16x32_bf16 v[76:79], v[112:115], v[220:223], v[76:79]
	v_mfma_f32_16x16x32_bf16 v[72:75], v[120:123], v[220:223], v[72:75]
	v_mfma_f32_16x16x32_bf16 v[148:151], v[116:119], v[194:197], v[148:151]
	v_mfma_f32_16x16x32_bf16 v[144:147], v[124:127], v[194:197], v[144:147]
	v_mfma_f32_16x16x32_bf16 v[108:111], v[116:119], v[208:211], v[108:111]
	v_mfma_f32_16x16x32_bf16 v[104:107], v[124:127], v[208:211], v[104:107]
	v_mfma_f32_16x16x32_bf16 v[92:95], v[116:119], v[216:219], v[92:95]
	v_mfma_f32_16x16x32_bf16 v[88:91], v[124:127], v[216:219], v[88:91]
	v_mfma_f32_16x16x32_bf16 v[76:79], v[116:119], v[224:227], v[76:79]
	v_mfma_f32_16x16x32_bf16 v[72:75], v[124:127], v[224:227], v[72:75]
	v_mfma_f32_16x16x32_bf16 v[140:143], v[128:131], v[172:175], v[140:143]
	v_mfma_f32_16x16x32_bf16 v[136:139], v[164:167], v[172:175], v[136:139]
	v_mfma_f32_16x16x32_bf16 v[100:103], v[128:131], v[204:207], v[100:103]
	v_mfma_f32_16x16x32_bf16 v[96:99], v[164:167], v[204:207], v[96:99]
	v_mfma_f32_16x16x32_bf16 v[84:87], v[128:131], v[212:215], v[84:87]
	v_mfma_f32_16x16x32_bf16 v[80:83], v[164:167], v[212:215], v[80:83]
	v_mfma_f32_16x16x32_bf16 v[68:71], v[128:131], v[220:223], v[68:71]
	v_mfma_f32_16x16x32_bf16 v[64:67], v[164:167], v[220:223], v[64:67]
	v_mfma_f32_16x16x32_bf16 v[140:143], v[132:135], v[194:197], v[140:143]
	v_mfma_f32_16x16x32_bf16 v[136:139], v[168:171], v[194:197], v[136:139]
	v_mfma_f32_16x16x32_bf16 v[100:103], v[132:135], v[208:211], v[100:103]
	v_mfma_f32_16x16x32_bf16 v[96:99], v[168:171], v[208:211], v[96:99]
	v_mfma_f32_16x16x32_bf16 v[84:87], v[132:135], v[216:219], v[84:87]
	v_mfma_f32_16x16x32_bf16 v[80:83], v[168:171], v[216:219], v[80:83]
	v_mfma_f32_16x16x32_bf16 v[68:71], v[132:135], v[224:227], v[68:71]
	v_mfma_f32_16x16x32_bf16 v[64:67], v[168:171], v[224:227], v[64:67]
	s_barrier
	s_add_i32 s56, s56, s20
	v_lshl_add_u64 v[178:179], s[50:51], 0, v[156:157]
	s_mov_b32 m0, s56
	ds_read_b128 v[172:175], v203 offset:16384
	ds_read_b128 v[194:197], v203 offset:17408
	ds_read_b128 v[204:207], v203 offset:18432
	ds_read_b128 v[208:211], v203 offset:19456
	ds_read_b128 v[212:215], v203 offset:20480
	ds_read_b128 v[216:219], v203 offset:21504
	ds_read_b128 v[220:223], v203 offset:22528
	ds_read_b128 v[224:227], v203 offset:23552
	global_load_lds_dwordx4 v[178:179], off
	s_add_i32 m0, s56, 0x2000
	s_add_u32 s56, s50, 0x40000
	v_lshl_add_u64 v[198:199], s[50:51], 0, v[152:153]
	s_addc_u32 s57, s51, 0
	s_add_i32 s58, s58, s20
	global_load_lds_dwordx4 v[198:199], off
	v_lshl_add_u64 v[228:229], s[56:57], 0, v[156:157]
	s_mov_b32 m0, s58
	v_lshl_add_u64 v[230:231], s[52:53], 0, v[154:155]
	global_load_lds_dwordx4 v[228:229], off
	v_lshl_add_u64 v[228:229], s[56:57], 0, v[152:153]
	s_add_i32 m0, s58, 0x2000
	s_nop 0
	global_load_lds_dwordx4 v[228:229], off
	v_lshl_add_u64 v[228:229], s[52:53], 0, v[158:159]
	s_mov_b32 m0, s21
	s_nop 0
	global_load_lds_dwordx4 v[228:229], off
	s_mov_b32 m0, s22
	s_nop 0
	global_load_lds_dwordx4 v[230:231], off
	s_waitcnt vmcnt(8)
	s_waitcnt lgkmcnt(0)
	s_barrier
; #define PG8_STAGE(bufoff, gbase, voff) do { _Pragma("unroll") for (int _i = 0; _i < 2; ++_i) \
;         __builtin_amdgcn_global_load_lds((const unsigned*)((const char*)(gbase) + (voff)[_i]), (PG8_LAS unsigned*)(lds + (bufoff) + ldsw + _i * 8192), 16, 0, 0); } while (0)
; #define PG8_LDA(dst, b, h) do { _Pragma("unroll") for (int m = 0; m < 4; ++m) _Pragma("unroll") for (int k = 0; k < 2; ++k) dst[m][k] = *(const PG8_LAS bf16x8*)(lds + PG8_SA(b, h) + aoff + m * 2048 + k * 1024); } while (0)
; #define PG8_LDB(dst, b, h) do { _Pragma("unroll") for (int n = 0; n < 2; ++n) _Pragma("unroll") for (int k = 0; k < 2; ++k) dst[n][k] = *(const PG8_LAS bf16x8*)(lds + PG8_SB(b, h) + boff + n * 2048 + k * 1024); } while (0)
; #define PG8_MMA(ai, bj, At, Bt) do { __builtin_amdgcn_s_setprio(1); _Pragma("unroll") for (int m = 0; m < 4; ++m) _Pragma("unroll") for (int n = 0; n < 2; ++n) _Pragma("unroll") for (int k = 0; k < 2; ++k) \
;         acc[ai][bj][m][n] = __builtin_amdgcn_mfma_f32_16x16x32_bf16(Bt[n][k], At[m][k], acc[ai][bj][m][n], 0, 0, 0); __builtin_amdgcn_s_setprio(0); } while (0)
; #define PG8_WAIT_V(n) asm volatile("s_waitcnt vmcnt(" #n ")" ::: "memory")
; #define PG8_WAIT_L(n) asm volatile("s_waitcnt lgkmcnt(" #n ")" ::: "memory")
; #define PG8_BAR __builtin_amdgcn_s_barrier()
; #define PG8_SCHED __builtin_amdgcn_sched_barrier(0)
; template <class Epi, class Sched, bool ALIGN_EPI = false, bool SP2 = false>
; __device__ __forceinline__ void gemm_phase(PG8_LAS unsigned char* lds, const Gemm g, const Sched& S, const Epi& E) {
;     ...
;             PG8_WAIT_V(8); PG8_WAIT_L(0); PG8_BAR; PG8_MMA(1, 0, At, B0); PG8_MMA(1, 1, At, B1); PG8_BAR; PG8_SCHED;
;             PG8_LDB(B0, 1, 0); PG8_LDB(B1, 1, 1); PG8_SCHED; PG8_LDA(At, 1, 0); PG8_STAGE(PG8_SA(0, 1), a2 + hstep, voffA);
;             PG8_WAIT_V(8); PG8_WAIT_L(0); PG8_BAR; PG8_MMA(0, 0, At, B0); PG8_MMA(0, 1, At, B1); PG8_BAR; PG8_SCHED;
;             PG8_LDA(At, 1, 1); PG8_STAGE(PG8_SB(1, 0), b3, voffB); PG8_STAGE(PG8_SB(1, 1), b3 + hstep, voffB); PG8_STAGE(PG8_SA(1, 0), a3, voffA);
	s_waitcnt lgkmcnt(0)
	v_mfma_f32_16x16x32_bf16 v[60:63], v[112:115], v[172:175], v[60:63]
	v_mfma_f32_16x16x32_bf16 v[56:59], v[120:123], v[172:175], v[56:59]
	v_mfma_f32_16x16x32_bf16 v[44:47], v[112:115], v[204:207], v[44:47]
	v_mfma_f32_16x16x32_bf16 v[40:43], v[120:123], v[204:207], v[40:43]
	v_mfma_f32_16x16x32_bf16 v[28:31], v[112:115], v[212:215], v[28:31]
	v_mfma_f32_16x16x32_bf16 v[24:27], v[120:123], v[212:215], v[24:27]
	v_mfma_f32_16x16x32_bf16 v[12:15], v[112:115], v[220:223], v[12:15]
	v_mfma_f32_16x16x32_bf16 v[8:11], v[120:123], v[220:223], v[8:11]
	v_mfma_f32_16x16x32_bf16 v[60:63], v[116:119], v[194:197], v[60:63]
	v_mfma_f32_16x16x32_bf16 v[56:59], v[124:127], v[194:197], v[56:59]
	v_mfma_f32_16x16x32_bf16 v[44:47], v[116:119], v[208:211], v[44:47]
	v_mfma_f32_16x16x32_bf16 v[40:43], v[124:127], v[208:211], v[40:43]
	v_mfma_f32_16x16x32_bf16 v[28:31], v[116:119], v[216:219], v[28:31]
	v_mfma_f32_16x16x32_bf16 v[24:27], v[124:127], v[216:219], v[24:27]
	v_mfma_f32_16x16x32_bf16 v[12:15], v[116:119], v[224:227], v[12:15]
	v_mfma_f32_16x16x32_bf16 v[8:11], v[124:127], v[224:227], v[8:11]
	v_mfma_f32_16x16x32_bf16 v[52:55], v[128:131], v[172:175], v[52:55]
	v_mfma_f32_16x16x32_bf16 v[48:51], v[164:167], v[172:175], v[48:51]
	v_mfma_f32_16x16x32_bf16 v[36:39], v[128:131], v[204:207], v[36:39]
	v_mfma_f32_16x16x32_bf16 v[32:35], v[164:167], v[204:207], v[32:35]
	v_mfma_f32_16x16x32_bf16 v[20:23], v[128:131], v[212:215], v[20:23]
	v_mfma_f32_16x16x32_bf16 v[16:19], v[164:167], v[212:215], v[16:19]
	v_mfma_f32_16x16x32_bf16 v[4:7], v[128:131], v[220:223], v[4:7]
	v_mfma_f32_16x16x32_bf16 v[0:3], v[164:167], v[220:223], v[0:3]
	v_mfma_f32_16x16x32_bf16 v[52:55], v[132:135], v[194:197], v[52:55]
	v_mfma_f32_16x16x32_bf16 v[48:51], v[168:171], v[194:197], v[48:51]
	v_mfma_f32_16x16x32_bf16 v[36:39], v[132:135], v[208:211], v[36:39]
	v_mfma_f32_16x16x32_bf16 v[32:35], v[168:171], v[208:211], v[32:35]
	v_mfma_f32_16x16x32_bf16 v[20:23], v[132:135], v[216:219], v[20:23]
	v_mfma_f32_16x16x32_bf16 v[16:19], v[168:171], v[216:219], v[16:19]
	v_mfma_f32_16x16x32_bf16 v[4:7], v[132:135], v[224:227], v[4:7]
	v_mfma_f32_16x16x32_bf16 v[0:3], v[168:171], v[224:227], v[0:3]
	s_barrier
	s_add_i32 s56, 0, 0x18000
	s_add_i32 s57, 0, 0x1c000
	v_add_u32_e32 v124, s56, v201
	v_add_u32_e32 v168, s57, v201
	ds_read_b128 v[112:115], v124
	ds_read_b128 v[116:119], v124 offset:1024
	ds_read_b128 v[120:123], v124 offset:2048
	ds_read_b128 v[124:127], v124 offset:3072
	ds_read_b128 v[128:131], v168
	ds_read_b128 v[132:135], v168 offset:1024
	ds_read_b128 v[164:167], v168 offset:2048
	ds_read_b128 v[168:171], v168 offset:3072
	s_add_u32 s52, s52, 0x40000
	s_addc_u32 s53, s53, 0
	s_mov_b32 m0, s23
	v_lshl_add_u64 v[232:233], s[52:53], 0, v[158:159]
	ds_read_b128 v[172:175], v203 offset:32768
	ds_read_b128 v[194:197], v203 offset:33792
	ds_read_b128 v[204:207], v203 offset:34816
	ds_read_b128 v[208:211], v203 offset:35840
	ds_read_b128 v[212:215], v203 offset:36864
	ds_read_b128 v[216:219], v203 offset:37888
	ds_read_b128 v[220:223], v203 offset:38912
	ds_read_b128 v[224:227], v203 offset:39936
	global_load_lds_dwordx4 v[232:233], off
	v_lshl_add_u64 v[232:233], s[52:53], 0, v[154:155]
	s_mov_b32 m0, s24
	s_nop 0
	global_load_lds_dwordx4 v[232:233], off
	s_waitcnt vmcnt(8)
	s_waitcnt lgkmcnt(0)
	s_barrier
	s_waitcnt lgkmcnt(0)
	v_mfma_f32_16x16x32_bf16 v[148:151], v[112:115], v[172:175], v[148:151]
	v_mfma_f32_16x16x32_bf16 v[144:147], v[120:123], v[172:175], v[144:147]
	v_mfma_f32_16x16x32_bf16 v[108:111], v[112:115], v[204:207], v[108:111]
	v_mfma_f32_16x16x32_bf16 v[104:107], v[120:123], v[204:207], v[104:107]
	v_mfma_f32_16x16x32_bf16 v[92:95], v[112:115], v[212:215], v[92:95]
	v_mfma_f32_16x16x32_bf16 v[88:91], v[120:123], v[212:215], v[88:91]
	v_mfma_f32_16x16x32_bf16 v[76:79], v[112:115], v[220:223], v[76:79]
	v_mfma_f32_16x16x32_bf16 v[72:75], v[120:123], v[220:223], v[72:75]
	v_mfma_f32_16x16x32_bf16 v[148:151], v[116:119], v[194:197], v[148:151]
	v_mfma_f32_16x16x32_bf16 v[144:147], v[124:127], v[194:197], v[144:147]
	v_mfma_f32_16x16x32_bf16 v[108:111], v[116:119], v[208:211], v[108:111]
	v_mfma_f32_16x16x32_bf16 v[104:107], v[124:127], v[208:211], v[104:107]
	v_mfma_f32_16x16x32_bf16 v[92:95], v[116:119], v[216:219], v[92:95]
	v_mfma_f32_16x16x32_bf16 v[88:91], v[124:127], v[216:219], v[88:91]
	v_mfma_f32_16x16x32_bf16 v[76:79], v[116:119], v[224:227], v[76:79]
	v_mfma_f32_16x16x32_bf16 v[72:75], v[124:127], v[224:227], v[72:75]
	v_mfma_f32_16x16x32_bf16 v[140:143], v[128:131], v[172:175], v[140:143]
	v_mfma_f32_16x16x32_bf16 v[136:139], v[164:167], v[172:175], v[136:139]
	v_mfma_f32_16x16x32_bf16 v[100:103], v[128:131], v[204:207], v[100:103]
	v_mfma_f32_16x16x32_bf16 v[96:99], v[164:167], v[204:207], v[96:99]
	v_mfma_f32_16x16x32_bf16 v[84:87], v[128:131], v[212:215], v[84:87]
	v_mfma_f32_16x16x32_bf16 v[80:83], v[164:167], v[212:215], v[80:83]
	v_mfma_f32_16x16x32_bf16 v[68:71], v[128:131], v[220:223], v[68:71]
	v_mfma_f32_16x16x32_bf16 v[64:67], v[164:167], v[220:223], v[64:67]
	v_mfma_f32_16x16x32_bf16 v[140:143], v[132:135], v[194:197], v[140:143]
	v_mfma_f32_16x16x32_bf16 v[136:139], v[168:171], v[194:197], v[136:139]
	v_mfma_f32_16x16x32_bf16 v[100:103], v[132:135], v[208:211], v[100:103]
	v_mfma_f32_16x16x32_bf16 v[96:99], v[168:171], v[208:211], v[96:99]
	v_mfma_f32_16x16x32_bf16 v[84:87], v[132:135], v[216:219], v[84:87]
	v_mfma_f32_16x16x32_bf16 v[80:83], v[168:171], v[216:219], v[80:83]
	v_mfma_f32_16x16x32_bf16 v[68:71], v[132:135], v[224:227], v[68:71]
	v_mfma_f32_16x16x32_bf16 v[64:67], v[168:171], v[224:227], v[64:67]
	s_barrier
; #define PG8_STAGE(bufoff, gbase, voff) do { _Pragma("unroll") for (int _i = 0; _i < 2; ++_i) \
;         __builtin_amdgcn_global_load_lds((const unsigned*)((const char*)(gbase) + (voff)[_i]), (PG8_LAS unsigned*)(lds + (bufoff) + ldsw + _i * 8192), 16, 0, 0); } while (0)
; #define PG8_LDA(dst, b, h) do { _Pragma("unroll") for (int m = 0; m < 4; ++m) _Pragma("unroll") for (int k = 0; k < 2; ++k) dst[m][k] = *(const PG8_LAS bf16x8*)(lds + PG8_SA(b, h) + aoff + m * 2048 + k * 1024); } while (0)
; #define PG8_MMA(ai, bj, At, Bt) do { __builtin_amdgcn_s_setprio(1); _Pragma("unroll") for (int m = 0; m < 4; ++m) _Pragma("unroll") for (int n = 0; n < 2; ++n) _Pragma("unroll") for (int k = 0; k < 2; ++k) \
;         acc[ai][bj][m][n] = __builtin_amdgcn_mfma_f32_16x16x32_bf16(Bt[n][k], At[m][k], acc[ai][bj][m][n], 0, 0, 0); __builtin_amdgcn_s_setprio(0); } while (0)
; #define PG8_WAIT_V(n) asm volatile("s_waitcnt vmcnt(" #n ")" ::: "memory")
; #define PG8_WAIT_L(n) asm volatile("s_waitcnt lgkmcnt(" #n ")" ::: "memory")
; #define PG8_BAR __builtin_amdgcn_s_barrier()
; #define PG8_SCHED __builtin_amdgcn_sched_barrier(0)
; template <class Epi, class Sched, bool ALIGN_EPI = false, bool SP2 = false>
; __device__ __forceinline__ void gemm_phase(PG8_LAS unsigned char* lds, const Gemm g, const Sched& S, const Epi& E) {
;     ...
;             PG8_LDA(At, 1, 1); PG8_STAGE(PG8_SB(1, 0), b3, voffB); PG8_STAGE(PG8_SB(1, 1), b3 + hstep, voffB); PG8_STAGE(PG8_SA(1, 0), a3, voffA);
;             PG8_WAIT_V(8); PG8_WAIT_L(0); PG8_BAR; PG8_MMA(1, 0, At, B0); PG8_MMA(1, 1, At, B1); PG8_BAR; PG8_SCHED;
;     ...
;         if constexpr (ALIGN_EPI) { if (wr == 0) PG8_BAR; }
	s_add_i32 s52, s56, s20
	v_lshl_add_u64 v[178:179], v[178:179], 0, s[36:37]
	s_mov_b32 m0, s52
	ds_read_b128 v[172:175], v203 offset:49152
	ds_read_b128 v[194:197], v203 offset:50176
	ds_read_b128 v[204:207], v203 offset:51200
	ds_read_b128 v[208:211], v203 offset:52224
	ds_read_b128 v[212:215], v203 offset:53248
	ds_read_b128 v[216:219], v203 offset:54272
	ds_read_b128 v[220:223], v203 offset:55296
	ds_read_b128 v[224:227], v203 offset:56320
	global_load_lds_dwordx4 v[178:179], off
	s_add_i32 m0, s52, 0x2000
	s_add_u32 s50, s50, 0x40080
	v_lshl_add_u64 v[178:179], v[198:199], 0, s[36:37]
	s_addc_u32 s51, s51, 0
	s_add_i32 s52, s57, s20
	global_load_lds_dwordx4 v[178:179], off
	v_lshl_add_u64 v[178:179], s[50:51], 0, v[156:157]
	s_mov_b32 m0, s52
	s_nop 0
	global_load_lds_dwordx4 v[178:179], off
	v_lshl_add_u64 v[178:179], s[50:51], 0, v[152:153]
	s_add_i32 m0, s52, 0x2000
	s_nop 0
	global_load_lds_dwordx4 v[178:179], off
	v_lshl_add_u64 v[178:179], v[228:229], 0, s[36:37]
	s_mov_b32 m0, s28
	s_nop 0
	global_load_lds_dwordx4 v[178:179], off
	v_lshl_add_u64 v[178:179], v[230:231], 0, s[36:37]
	s_mov_b32 m0, s29
	s_nop 0
	global_load_lds_dwordx4 v[178:179], off
	s_waitcnt vmcnt(8)
	s_waitcnt lgkmcnt(0)
	s_barrier
	s_waitcnt lgkmcnt(0)
	v_mfma_f32_16x16x32_bf16 v[60:63], v[112:115], v[172:175], v[60:63]
	v_mfma_f32_16x16x32_bf16 v[56:59], v[120:123], v[172:175], v[56:59]
	v_mfma_f32_16x16x32_bf16 v[44:47], v[112:115], v[204:207], v[44:47]
	v_mfma_f32_16x16x32_bf16 v[40:43], v[120:123], v[204:207], v[40:43]
	v_mfma_f32_16x16x32_bf16 v[28:31], v[112:115], v[212:215], v[28:31]
	v_mfma_f32_16x16x32_bf16 v[24:27], v[120:123], v[212:215], v[24:27]
	v_mfma_f32_16x16x32_bf16 v[12:15], v[112:115], v[220:223], v[12:15]
	v_mfma_f32_16x16x32_bf16 v[8:11], v[120:123], v[220:223], v[8:11]
	v_mfma_f32_16x16x32_bf16 v[60:63], v[116:119], v[194:197], v[60:63]
	v_mfma_f32_16x16x32_bf16 v[56:59], v[124:127], v[194:197], v[56:59]
	v_mfma_f32_16x16x32_bf16 v[44:47], v[116:119], v[208:211], v[44:47]
	v_mfma_f32_16x16x32_bf16 v[40:43], v[124:127], v[208:211], v[40:43]
	v_mfma_f32_16x16x32_bf16 v[28:31], v[116:119], v[216:219], v[28:31]
	v_mfma_f32_16x16x32_bf16 v[24:27], v[124:127], v[216:219], v[24:27]
	v_mfma_f32_16x16x32_bf16 v[12:15], v[116:119], v[224:227], v[12:15]
	v_mfma_f32_16x16x32_bf16 v[8:11], v[124:127], v[224:227], v[8:11]
	v_mfma_f32_16x16x32_bf16 v[52:55], v[128:131], v[172:175], v[52:55]
	v_mfma_f32_16x16x32_bf16 v[48:51], v[164:167], v[172:175], v[48:51]
	v_mfma_f32_16x16x32_bf16 v[36:39], v[128:131], v[204:207], v[36:39]
	v_mfma_f32_16x16x32_bf16 v[32:35], v[164:167], v[204:207], v[32:35]
	v_mfma_f32_16x16x32_bf16 v[20:23], v[128:131], v[212:215], v[20:23]
	v_mfma_f32_16x16x32_bf16 v[16:19], v[164:167], v[212:215], v[16:19]
	v_mfma_f32_16x16x32_bf16 v[4:7], v[128:131], v[220:223], v[4:7]
	v_mfma_f32_16x16x32_bf16 v[0:3], v[164:167], v[220:223], v[0:3]
	v_mfma_f32_16x16x32_bf16 v[52:55], v[132:135], v[194:197], v[52:55]
	v_mfma_f32_16x16x32_bf16 v[48:51], v[168:171], v[194:197], v[48:51]
	v_mfma_f32_16x16x32_bf16 v[36:39], v[132:135], v[208:211], v[36:39]
	v_mfma_f32_16x16x32_bf16 v[32:35], v[168:171], v[208:211], v[32:35]
	v_mfma_f32_16x16x32_bf16 v[20:23], v[132:135], v[216:219], v[20:23]
	v_mfma_f32_16x16x32_bf16 v[16:19], v[168:171], v[216:219], v[16:19]
	v_mfma_f32_16x16x32_bf16 v[4:7], v[132:135], v[224:227], v[4:7]
	v_mfma_f32_16x16x32_bf16 v[0:3], v[168:171], v[224:227], v[0:3]
	s_barrier
	s_add_i32 s55, s55, 2
	s_add_u32 s43, s43, 0x100
	s_addc_u32 s54, s54, 0
	s_add_u32 s48, s48, 0x100
	s_addc_u32 s49, s49, 0
	s_cmp_gt_u32 s55, 13
	s_cbranch_scc0 .LBB0_558
	s_and_b64 vcc, exec, s[26:27]
	s_cbranch_vccz .LBB0_561
	s_barrier

; #define PG8_STAGE(bufoff, gbase, voff) do { _Pragma("unroll") for (int _i = 0; _i < 2; ++_i) \
;         __builtin_amdgcn_global_load_lds((const unsigned*)((const char*)(gbase) + (voff)[_i]), (PG8_LAS unsigned*)(lds + (bufoff) + ldsw + _i * 8192), 16, 0, 0); } while (0)
; #define PG8_LDA(dst, b, h) do { _Pragma("unroll") for (int m = 0; m < 4; ++m) _Pragma("unroll") for (int k = 0; k < 2; ++k) dst[m][k] = *(const PG8_LAS bf16x8*)(lds + PG8_SA(b, h) + aoff + m * 2048 + k * 1024); } while (0)
; #define PG8_LDB(dst, b, h) do { _Pragma("unroll") for (int n = 0; n < 2; ++n) _Pragma("unroll") for (int k = 0; k < 2; ++k) dst[n][k] = *(const PG8_LAS bf16x8*)(lds + PG8_SB(b, h) + boff + n * 2048 + k * 1024); } while (0)
; #define PG8_WAIT_V(n) asm volatile("s_waitcnt vmcnt(" #n ")" ::: "memory")
; #define PG8_WAIT_L(n) asm volatile("s_waitcnt lgkmcnt(" #n ")" ::: "memory")
; #define PG8_BAR __builtin_amdgcn_s_barrier()
; #define PG8_SCHED __builtin_amdgcn_sched_barrier(0)
; template <class Epi, class Sched, bool ALIGN_EPI = false, bool SP2 = false>
; __device__ __forceinline__ void gemm_phase(PG8_LAS unsigned char* lds, const Gemm g, const Sched& S, const Epi& E) {
;     ...
;         const bool has_next = S.next(ui + 1, nxt);
;         const char* nA = has_next ? (const char*)g.A + (size_t)nxt.pm * tstep : cA; const char* nB = has_next ? (const char*)g.Bt + (size_t)nxt.pn * tstep : cB;
;         for (int t = 0; t < nt; t += 2) {
;             const bool last = (t == nt - 2);
;             const char* a1 = cA + (size_t)(t + 1) * kstep;
;             const char* a2 = last ? nA : cA + (size_t)(t + 2) * kstep; const char* b2 = last ? nB : cB + (size_t)(t + 2) * kstep;
;             const char* a3 = a2 + kstep; const char* b3 = b2 + kstep;
;             if (last && has_next) S.a_ready(nxt);
;             if constexpr (SP2) {
;             PG8_LDB(B0, 0, 0); PG8_LDB(B1, 0, 1); PG8_SCHED; PG8_LDA(At, 0, 0); PG8_STAGE(PG8_SA(1, 1), a1 + hstep, voffA);
;             PG8_WAIT_V(8); PG8_WAIT_L(0); PG8_BAR; PG8_MMA(0, 0, At, B0); PG8_MMA(0, 1, At, B1); PG8_BAR; PG8_SCHED;
;             PG8_LDA(At, 0, 1); PG8_STAGE(PG8_SB(0, 0), b2, voffB); PG8_STAGE(PG8_SB(0, 1), b2 + hstep, voffB); PG8_STAGE(PG8_SA(0, 0), a2, voffA);
;             PG8_WAIT_V(8); PG8_WAIT_L(0); PG8_BAR; PG8_MMA(1, 0, At, B0); PG8_MMA(1, 1, At, B1); PG8_BAR; PG8_SCHED;
.LBB0_659:
	s_add_u32 s48, s46, 0xfffc0080
	s_addc_u32 s49, s47, -1
	s_add_i32 s54, 0, 0x10000
	s_cmp_eq_u32 s53, 12
	s_cselect_b32 s51, s33, s49
	s_cselect_b32 s50, s34, s48
	v_add_u32_e32 v141, s54, v148
	s_cselect_b32 s49, s27, s52
	s_cselect_b32 s48, s35, s41
	s_add_i32 s56, 0, 0x14000
	ds_read_b128 v[142:145], v141
	ds_read_b128 v[152:155], v141 offset:1024
	ds_read_b128 v[156:159], v141 offset:2048
	ds_read_b128 v[160:163], v141 offset:3072
	v_add_u32_e32 v141, s56, v148
	ds_read_b128 v[164:167], v141
	ds_read_b128 v[168:171], v141 offset:1024
	ds_read_b128 v[172:175], v141 offset:2048
	ds_read_b128 v[194:197], v141 offset:3072
	v_lshl_add_u64 v[178:179], s[46:47], 0, v[138:139]
	s_add_i32 m0, s21, 0xc000
	ds_read_b128 v[198:201], v151
	ds_read_b128 v[202:205], v151 offset:1024
	ds_read_b128 v[206:209], v151 offset:2048
	ds_read_b128 v[210:213], v151 offset:3072
	ds_read_b128 v[214:217], v151 offset:4096
	ds_read_b128 v[218:221], v151 offset:5120
	ds_read_b128 v[222:225], v151 offset:6144
	ds_read_b128 v[226:229], v151 offset:7168
	global_load_lds_dwordx4 v[178:179], off
	v_lshl_add_u64 v[178:179], s[46:47], 0, v[136:137]
	s_add_i32 m0, s21, 0xe000
	s_nop 0
	global_load_lds_dwordx4 v[178:179], off
	s_waitcnt vmcnt(8)
	s_waitcnt lgkmcnt(0)
	s_barrier
	s_waitcnt lgkmcnt(0)
	v_mfma_f32_16x16x32_bf16 v[124:127], v[142:145], v[198:201], v[124:127]
	v_mfma_f32_16x16x32_bf16 v[120:123], v[156:159], v[198:201], v[120:123]
	v_mfma_f32_16x16x32_bf16 v[108:111], v[142:145], v[206:209], v[108:111]
	v_mfma_f32_16x16x32_bf16 v[104:107], v[156:159], v[206:209], v[104:107]
	v_mfma_f32_16x16x32_bf16 v[92:95], v[142:145], v[214:217], v[92:95]
	v_mfma_f32_16x16x32_bf16 v[88:91], v[156:159], v[214:217], v[88:91]
	v_mfma_f32_16x16x32_bf16 v[76:79], v[142:145], v[222:225], v[76:79]
	v_mfma_f32_16x16x32_bf16 v[72:75], v[156:159], v[222:225], v[72:75]
	v_mfma_f32_16x16x32_bf16 v[124:127], v[152:155], v[202:205], v[124:127]
	v_mfma_f32_16x16x32_bf16 v[120:123], v[160:163], v[202:205], v[120:123]
	v_mfma_f32_16x16x32_bf16 v[108:111], v[152:155], v[210:213], v[108:111]
	v_mfma_f32_16x16x32_bf16 v[104:107], v[160:163], v[210:213], v[104:107]
	v_mfma_f32_16x16x32_bf16 v[92:95], v[152:155], v[218:221], v[92:95]
	v_mfma_f32_16x16x32_bf16 v[88:91], v[160:163], v[218:221], v[88:91]
	v_mfma_f32_16x16x32_bf16 v[76:79], v[152:155], v[226:229], v[76:79]
	v_mfma_f32_16x16x32_bf16 v[72:75], v[160:163], v[226:229], v[72:75]
	v_mfma_f32_16x16x32_bf16 v[116:119], v[164:167], v[198:201], v[116:119]
	v_mfma_f32_16x16x32_bf16 v[112:115], v[172:175], v[198:201], v[112:115]
	v_mfma_f32_16x16x32_bf16 v[100:103], v[164:167], v[206:209], v[100:103]
	v_mfma_f32_16x16x32_bf16 v[96:99], v[172:175], v[206:209], v[96:99]
	v_mfma_f32_16x16x32_bf16 v[84:87], v[164:167], v[214:217], v[84:87]
	v_mfma_f32_16x16x32_bf16 v[80:83], v[172:175], v[214:217], v[80:83]
	v_mfma_f32_16x16x32_bf16 v[68:71], v[164:167], v[222:225], v[68:71]
	v_mfma_f32_16x16x32_bf16 v[64:67], v[172:175], v[222:225], v[64:67]
	v_mfma_f32_16x16x32_bf16 v[116:119], v[168:171], v[202:205], v[116:119]
	v_mfma_f32_16x16x32_bf16 v[112:115], v[194:197], v[202:205], v[112:115]
	v_mfma_f32_16x16x32_bf16 v[100:103], v[168:171], v[210:213], v[100:103]
	v_mfma_f32_16x16x32_bf16 v[96:99], v[194:197], v[210:213], v[96:99]
	v_mfma_f32_16x16x32_bf16 v[84:87], v[168:171], v[218:221], v[84:87]
	v_mfma_f32_16x16x32_bf16 v[80:83], v[194:197], v[218:221], v[80:83]
	v_mfma_f32_16x16x32_bf16 v[68:71], v[168:171], v[226:229], v[68:71]
	v_mfma_f32_16x16x32_bf16 v[64:67], v[194:197], v[226:229], v[64:67]
	s_barrier
	s_add_i32 s54, s54, s20
	v_lshl_add_u64 v[178:179], s[48:49], 0, v[132:133]
	s_mov_b32 m0, s54
	ds_read_b128 v[198:201], v151 offset:16384
	ds_read_b128 v[202:205], v151 offset:17408
	ds_read_b128 v[206:209], v151 offset:18432
	ds_read_b128 v[210:213], v151 offset:19456
	ds_read_b128 v[214:217], v151 offset:20480
	ds_read_b128 v[218:221], v151 offset:21504
	ds_read_b128 v[222:225], v151 offset:22528
	ds_read_b128 v[226:229], v151 offset:23552
	global_load_lds_dwordx4 v[178:179], off
	s_add_i32 m0, s54, 0x2000
	s_add_u32 s54, s48, 0x40000
	v_lshl_add_u64 v[230:231], s[48:49], 0, v[128:129]
	s_addc_u32 s55, s49, 0
	s_add_i32 s56, s56, s20
	global_load_lds_dwordx4 v[230:231], off
	v_lshl_add_u64 v[232:233], s[54:55], 0, v[132:133]
	s_mov_b32 m0, s56
	v_lshl_add_u64 v[234:235], s[50:51], 0, v[130:131]
	global_load_lds_dwordx4 v[232:233], off
	v_lshl_add_u64 v[232:233], s[54:55], 0, v[128:129]
	s_add_i32 m0, s56, 0x2000
	s_nop 0
	global_load_lds_dwordx4 v[232:233], off
	v_lshl_add_u64 v[232:233], s[50:51], 0, v[134:135]
	s_mov_b32 m0, s21
	s_nop 0
	global_load_lds_dwordx4 v[232:233], off
	s_mov_b32 m0, s22
	s_nop 0
	global_load_lds_dwordx4 v[234:235], off
	s_waitcnt vmcnt(8)
	s_waitcnt lgkmcnt(0)
	s_barrier
; #define PG8_STAGE(bufoff, gbase, voff) do { _Pragma("unroll") for (int _i = 0; _i < 2; ++_i) \
;         __builtin_amdgcn_global_load_lds((const unsigned*)((const char*)(gbase) + (voff)[_i]), (PG8_LAS unsigned*)(lds + (bufoff) + ldsw + _i * 8192), 16, 0, 0); } while (0)
; #define PG8_LDA(dst, b, h) do { _Pragma("unroll") for (int m = 0; m < 4; ++m) _Pragma("unroll") for (int k = 0; k < 2; ++k) dst[m][k] = *(const PG8_LAS bf16x8*)(lds + PG8_SA(b, h) + aoff + m * 2048 + k * 1024); } while (0)
; #define PG8_LDB(dst, b, h) do { _Pragma("unroll") for (int n = 0; n < 2; ++n) _Pragma("unroll") for (int k = 0; k < 2; ++k) dst[n][k] = *(const PG8_LAS bf16x8*)(lds + PG8_SB(b, h) + boff + n * 2048 + k * 1024); } while (0)
; #define PG8_MMA(ai, bj, At, Bt) do { __builtin_amdgcn_s_setprio(1); _Pragma("unroll") for (int m = 0; m < 4; ++m) _Pragma("unroll") for (int n = 0; n < 2; ++n) _Pragma("unroll") for (int k = 0; k < 2; ++k) \
;         acc[ai][bj][m][n] = __builtin_amdgcn_mfma_f32_16x16x32_bf16(Bt[n][k], At[m][k], acc[ai][bj][m][n], 0, 0, 0); __builtin_amdgcn_s_setprio(0); } while (0)
; #define PG8_WAIT_V(n) asm volatile("s_waitcnt vmcnt(" #n ")" ::: "memory")
; #define PG8_WAIT_L(n) asm volatile("s_waitcnt lgkmcnt(" #n ")" ::: "memory")
; #define PG8_BAR __builtin_amdgcn_s_barrier()
; #define PG8_SCHED __builtin_amdgcn_sched_barrier(0)
; template <class Epi, class Sched, bool ALIGN_EPI = false, bool SP2 = false>
; __device__ __forceinline__ void gemm_phase(PG8_LAS unsigned char* lds, const Gemm g, const Sched& S, const Epi& E) {
;     ...
;             PG8_WAIT_V(8); PG8_WAIT_L(0); PG8_BAR; PG8_MMA(1, 0, At, B0); PG8_MMA(1, 1, At, B1); PG8_BAR; PG8_SCHED;
;             PG8_LDB(B0, 1, 0); PG8_LDB(B1, 1, 1); PG8_SCHED; PG8_LDA(At, 1, 0); PG8_STAGE(PG8_SA(0, 1), a2 + hstep, voffA);
;             PG8_WAIT_V(8); PG8_WAIT_L(0); PG8_BAR; PG8_MMA(0, 0, At, B0); PG8_MMA(0, 1, At, B1); PG8_BAR; PG8_SCHED;
;             PG8_LDA(At, 1, 1); PG8_STAGE(PG8_SB(1, 0), b3, voffB); PG8_STAGE(PG8_SB(1, 1), b3 + hstep, voffB); PG8_STAGE(PG8_SA(1, 0), a3, voffA);
	s_waitcnt lgkmcnt(0)
	v_mfma_f32_16x16x32_bf16 v[60:63], v[142:145], v[198:201], v[60:63]
	v_mfma_f32_16x16x32_bf16 v[56:59], v[156:159], v[198:201], v[56:59]
	v_mfma_f32_16x16x32_bf16 v[44:47], v[142:145], v[206:209], v[44:47]
	v_mfma_f32_16x16x32_bf16 v[40:43], v[156:159], v[206:209], v[40:43]
	v_mfma_f32_16x16x32_bf16 v[28:31], v[142:145], v[214:217], v[28:31]
	v_mfma_f32_16x16x32_bf16 v[24:27], v[156:159], v[214:217], v[24:27]
	v_mfma_f32_16x16x32_bf16 v[12:15], v[142:145], v[222:225], v[12:15]
	v_mfma_f32_16x16x32_bf16 v[8:11], v[156:159], v[222:225], v[8:11]
	v_mfma_f32_16x16x32_bf16 v[60:63], v[152:155], v[202:205], v[60:63]
	v_mfma_f32_16x16x32_bf16 v[56:59], v[160:163], v[202:205], v[56:59]
	v_mfma_f32_16x16x32_bf16 v[44:47], v[152:155], v[210:213], v[44:47]
	v_mfma_f32_16x16x32_bf16 v[40:43], v[160:163], v[210:213], v[40:43]
	v_mfma_f32_16x16x32_bf16 v[28:31], v[152:155], v[218:221], v[28:31]
	v_mfma_f32_16x16x32_bf16 v[24:27], v[160:163], v[218:221], v[24:27]
	v_mfma_f32_16x16x32_bf16 v[12:15], v[152:155], v[226:229], v[12:15]
	v_mfma_f32_16x16x32_bf16 v[8:11], v[160:163], v[226:229], v[8:11]
	v_mfma_f32_16x16x32_bf16 v[52:55], v[164:167], v[198:201], v[52:55]
	v_mfma_f32_16x16x32_bf16 v[48:51], v[172:175], v[198:201], v[48:51]
	v_mfma_f32_16x16x32_bf16 v[36:39], v[164:167], v[206:209], v[36:39]
	v_mfma_f32_16x16x32_bf16 v[32:35], v[172:175], v[206:209], v[32:35]
	v_mfma_f32_16x16x32_bf16 v[20:23], v[164:167], v[214:217], v[20:23]
	v_mfma_f32_16x16x32_bf16 v[16:19], v[172:175], v[214:217], v[16:19]
	v_mfma_f32_16x16x32_bf16 v[4:7], v[164:167], v[222:225], v[4:7]
	v_mfma_f32_16x16x32_bf16 v[0:3], v[172:175], v[222:225], v[0:3]
	v_mfma_f32_16x16x32_bf16 v[52:55], v[168:171], v[202:205], v[52:55]
	v_mfma_f32_16x16x32_bf16 v[48:51], v[194:197], v[202:205], v[48:51]
	v_mfma_f32_16x16x32_bf16 v[36:39], v[168:171], v[210:213], v[36:39]
	v_mfma_f32_16x16x32_bf16 v[32:35], v[194:197], v[210:213], v[32:35]
	v_mfma_f32_16x16x32_bf16 v[20:23], v[168:171], v[218:221], v[20:23]
	v_mfma_f32_16x16x32_bf16 v[16:19], v[194:197], v[218:221], v[16:19]
	v_mfma_f32_16x16x32_bf16 v[4:7], v[168:171], v[226:229], v[4:7]
	v_mfma_f32_16x16x32_bf16 v[0:3], v[194:197], v[226:229], v[0:3]
	s_barrier
	s_add_i32 s54, 0, 0x18000
	v_add_u32_e32 v141, s54, v148
	s_add_i32 s55, 0, 0x1c000
	ds_read_b128 v[142:145], v141
	ds_read_b128 v[152:155], v141 offset:1024
	ds_read_b128 v[156:159], v141 offset:2048
	ds_read_b128 v[160:163], v141 offset:3072
	v_add_u32_e32 v141, s55, v148
	ds_read_b128 v[164:167], v141
	ds_read_b128 v[168:171], v141 offset:1024
	ds_read_b128 v[172:175], v141 offset:2048
	ds_read_b128 v[194:197], v141 offset:3072
	s_add_u32 s50, s50, 0x40000
	s_addc_u32 s51, s51, 0
	s_mov_b32 m0, s23
	v_lshl_add_u64 v[236:237], s[50:51], 0, v[134:135]
	ds_read_b128 v[198:201], v151 offset:32768
	ds_read_b128 v[202:205], v151 offset:33792
	ds_read_b128 v[206:209], v151 offset:34816
	ds_read_b128 v[210:213], v151 offset:35840
	ds_read_b128 v[214:217], v151 offset:36864
	ds_read_b128 v[218:221], v151 offset:37888
	ds_read_b128 v[222:225], v151 offset:38912
	ds_read_b128 v[226:229], v151 offset:39936
	global_load_lds_dwordx4 v[236:237], off
	v_lshl_add_u64 v[236:237], s[50:51], 0, v[130:131]
	s_mov_b32 m0, s24
	s_nop 0
	global_load_lds_dwordx4 v[236:237], off
	s_waitcnt vmcnt(8)
	s_waitcnt lgkmcnt(0)
	s_barrier
	s_waitcnt lgkmcnt(0)
	v_mfma_f32_16x16x32_bf16 v[124:127], v[142:145], v[198:201], v[124:127]
	v_mfma_f32_16x16x32_bf16 v[120:123], v[156:159], v[198:201], v[120:123]
	v_mfma_f32_16x16x32_bf16 v[108:111], v[142:145], v[206:209], v[108:111]
	v_mfma_f32_16x16x32_bf16 v[104:107], v[156:159], v[206:209], v[104:107]
	v_mfma_f32_16x16x32_bf16 v[92:95], v[142:145], v[214:217], v[92:95]
	v_mfma_f32_16x16x32_bf16 v[88:91], v[156:159], v[214:217], v[88:91]
	v_mfma_f32_16x16x32_bf16 v[76:79], v[142:145], v[222:225], v[76:79]
	v_mfma_f32_16x16x32_bf16 v[72:75], v[156:159], v[222:225], v[72:75]
	v_mfma_f32_16x16x32_bf16 v[124:127], v[152:155], v[202:205], v[124:127]
	v_mfma_f32_16x16x32_bf16 v[120:123], v[160:163], v[202:205], v[120:123]
	v_mfma_f32_16x16x32_bf16 v[108:111], v[152:155], v[210:213], v[108:111]
	v_mfma_f32_16x16x32_bf16 v[104:107], v[160:163], v[210:213], v[104:107]
	v_mfma_f32_16x16x32_bf16 v[92:95], v[152:155], v[218:221], v[92:95]
	v_mfma_f32_16x16x32_bf16 v[88:91], v[160:163], v[218:221], v[88:91]
	v_mfma_f32_16x16x32_bf16 v[76:79], v[152:155], v[226:229], v[76:79]
	v_mfma_f32_16x16x32_bf16 v[72:75], v[160:163], v[226:229], v[72:75]
	v_mfma_f32_16x16x32_bf16 v[116:119], v[164:167], v[198:201], v[116:119]
	v_mfma_f32_16x16x32_bf16 v[112:115], v[172:175], v[198:201], v[112:115]
	v_mfma_f32_16x16x32_bf16 v[100:103], v[164:167], v[206:209], v[100:103]
	v_mfma_f32_16x16x32_bf16 v[96:99], v[172:175], v[206:209], v[96:99]
	v_mfma_f32_16x16x32_bf16 v[84:87], v[164:167], v[214:217], v[84:87]
	v_mfma_f32_16x16x32_bf16 v[80:83], v[172:175], v[214:217], v[80:83]
	v_mfma_f32_16x16x32_bf16 v[68:71], v[164:167], v[222:225], v[68:71]
	v_mfma_f32_16x16x32_bf16 v[64:67], v[172:175], v[222:225], v[64:67]
	v_mfma_f32_16x16x32_bf16 v[116:119], v[168:171], v[202:205], v[116:119]
	v_mfma_f32_16x16x32_bf16 v[112:115], v[194:197], v[202:205], v[112:115]
	v_mfma_f32_16x16x32_bf16 v[100:103], v[168:171], v[210:213], v[100:103]
	v_mfma_f32_16x16x32_bf16 v[96:99], v[194:197], v[210:213], v[96:99]
	v_mfma_f32_16x16x32_bf16 v[84:87], v[168:171], v[218:221], v[84:87]
	v_mfma_f32_16x16x32_bf16 v[80:83], v[194:197], v[218:221], v[80:83]
	v_mfma_f32_16x16x32_bf16 v[68:71], v[168:171], v[226:229], v[68:71]
	v_mfma_f32_16x16x32_bf16 v[64:67], v[194:197], v[226:229], v[64:67]
	s_barrier
; #define PG8_STAGE(bufoff, gbase, voff) do { _Pragma("unroll") for (int _i = 0; _i < 2; ++_i) \
;         __builtin_amdgcn_global_load_lds((const unsigned*)((const char*)(gbase) + (voff)[_i]), (PG8_LAS unsigned*)(lds + (bufoff) + ldsw + _i * 8192), 16, 0, 0); } while (0)
; #define PG8_LDA(dst, b, h) do { _Pragma("unroll") for (int m = 0; m < 4; ++m) _Pragma("unroll") for (int k = 0; k < 2; ++k) dst[m][k] = *(const PG8_LAS bf16x8*)(lds + PG8_SA(b, h) + aoff + m * 2048 + k * 1024); } while (0)
; #define PG8_MMA(ai, bj, At, Bt) do { __builtin_amdgcn_s_setprio(1); _Pragma("unroll") for (int m = 0; m < 4; ++m) _Pragma("unroll") for (int n = 0; n < 2; ++n) _Pragma("unroll") for (int k = 0; k < 2; ++k) \
;         acc[ai][bj][m][n] = __builtin_amdgcn_mfma_f32_16x16x32_bf16(Bt[n][k], At[m][k], acc[ai][bj][m][n], 0, 0, 0); __builtin_amdgcn_s_setprio(0); } while (0)
; #define PG8_WAIT_V(n) asm volatile("s_waitcnt vmcnt(" #n ")" ::: "memory")
; #define PG8_WAIT_L(n) asm volatile("s_waitcnt lgkmcnt(" #n ")" ::: "memory")
; #define PG8_BAR __builtin_amdgcn_s_barrier()
; #define PG8_SCHED __builtin_amdgcn_sched_barrier(0)
; template <class Epi, class Sched, bool ALIGN_EPI = false, bool SP2 = false>
; __device__ __forceinline__ void gemm_phase(PG8_LAS unsigned char* lds, const Gemm g, const Sched& S, const Epi& E) {
;     ...
;             PG8_LDA(At, 1, 1); PG8_STAGE(PG8_SB(1, 0), b3, voffB); PG8_STAGE(PG8_SB(1, 1), b3 + hstep, voffB); PG8_STAGE(PG8_SA(1, 0), a3, voffA);
;             PG8_WAIT_V(8); PG8_WAIT_L(0); PG8_BAR; PG8_MMA(1, 0, At, B0); PG8_MMA(1, 1, At, B1); PG8_BAR; PG8_SCHED;
;     ...
;         if constexpr (ALIGN_EPI) { if (wr == 0) PG8_BAR; }
	s_add_i32 s50, s54, s20
	v_lshl_add_u64 v[178:179], v[178:179], 0, s[36:37]
	s_mov_b32 m0, s50
	ds_read_b128 v[198:201], v151 offset:49152
	ds_read_b128 v[202:205], v151 offset:50176
	ds_read_b128 v[206:209], v151 offset:51200
	ds_read_b128 v[210:213], v151 offset:52224
	ds_read_b128 v[214:217], v151 offset:53248
	ds_read_b128 v[218:221], v151 offset:54272
	ds_read_b128 v[222:225], v151 offset:55296
	ds_read_b128 v[226:229], v151 offset:56320
	global_load_lds_dwordx4 v[178:179], off
	s_add_i32 m0, s50, 0x2000
	s_add_u32 s48, s48, 0x40080
	v_lshl_add_u64 v[178:179], v[230:231], 0, s[36:37]
	s_addc_u32 s49, s49, 0
	s_add_i32 s50, s55, s20
	global_load_lds_dwordx4 v[178:179], off
	v_lshl_add_u64 v[178:179], s[48:49], 0, v[132:133]
	s_mov_b32 m0, s50
	s_nop 0
	global_load_lds_dwordx4 v[178:179], off
	v_lshl_add_u64 v[178:179], s[48:49], 0, v[128:129]
	s_add_i32 m0, s50, 0x2000
	s_nop 0
	global_load_lds_dwordx4 v[178:179], off
	v_lshl_add_u64 v[178:179], v[232:233], 0, s[36:37]
	s_mov_b32 m0, s25
	s_nop 0
	global_load_lds_dwordx4 v[178:179], off
	v_lshl_add_u64 v[178:179], v[234:235], 0, s[36:37]
	s_mov_b32 m0, s28
	s_nop 0
	global_load_lds_dwordx4 v[178:179], off
	s_waitcnt vmcnt(8)
	s_waitcnt lgkmcnt(0)
	s_barrier
	s_waitcnt lgkmcnt(0)
	v_mfma_f32_16x16x32_bf16 v[60:63], v[142:145], v[198:201], v[60:63]
	v_mfma_f32_16x16x32_bf16 v[56:59], v[156:159], v[198:201], v[56:59]
	v_mfma_f32_16x16x32_bf16 v[44:47], v[142:145], v[206:209], v[44:47]
	v_mfma_f32_16x16x32_bf16 v[40:43], v[156:159], v[206:209], v[40:43]
	v_mfma_f32_16x16x32_bf16 v[28:31], v[142:145], v[214:217], v[28:31]
	v_mfma_f32_16x16x32_bf16 v[24:27], v[156:159], v[214:217], v[24:27]
	v_mfma_f32_16x16x32_bf16 v[12:15], v[142:145], v[222:225], v[12:15]
	v_mfma_f32_16x16x32_bf16 v[8:11], v[156:159], v[222:225], v[8:11]
	v_mfma_f32_16x16x32_bf16 v[60:63], v[152:155], v[202:205], v[60:63]
	v_mfma_f32_16x16x32_bf16 v[56:59], v[160:163], v[202:205], v[56:59]
	v_mfma_f32_16x16x32_bf16 v[44:47], v[152:155], v[210:213], v[44:47]
	v_mfma_f32_16x16x32_bf16 v[40:43], v[160:163], v[210:213], v[40:43]
	v_mfma_f32_16x16x32_bf16 v[28:31], v[152:155], v[218:221], v[28:31]
	v_mfma_f32_16x16x32_bf16 v[24:27], v[160:163], v[218:221], v[24:27]
	v_mfma_f32_16x16x32_bf16 v[12:15], v[152:155], v[226:229], v[12:15]
	v_mfma_f32_16x16x32_bf16 v[8:11], v[160:163], v[226:229], v[8:11]
	v_mfma_f32_16x16x32_bf16 v[52:55], v[164:167], v[198:201], v[52:55]
	v_mfma_f32_16x16x32_bf16 v[48:51], v[172:175], v[198:201], v[48:51]
	v_mfma_f32_16x16x32_bf16 v[36:39], v[164:167], v[206:209], v[36:39]
	v_mfma_f32_16x16x32_bf16 v[32:35], v[172:175], v[206:209], v[32:35]
	v_mfma_f32_16x16x32_bf16 v[20:23], v[164:167], v[214:217], v[20:23]
	v_mfma_f32_16x16x32_bf16 v[16:19], v[172:175], v[214:217], v[16:19]
	v_mfma_f32_16x16x32_bf16 v[4:7], v[164:167], v[222:225], v[4:7]
	v_mfma_f32_16x16x32_bf16 v[0:3], v[172:175], v[222:225], v[0:3]
	v_mfma_f32_16x16x32_bf16 v[52:55], v[168:171], v[202:205], v[52:55]
	v_mfma_f32_16x16x32_bf16 v[48:51], v[194:197], v[202:205], v[48:51]
	v_mfma_f32_16x16x32_bf16 v[36:39], v[168:171], v[210:213], v[36:39]
	v_mfma_f32_16x16x32_bf16 v[32:35], v[194:197], v[210:213], v[32:35]
	v_mfma_f32_16x16x32_bf16 v[20:23], v[168:171], v[218:221], v[20:23]
	v_mfma_f32_16x16x32_bf16 v[16:19], v[194:197], v[218:221], v[16:19]
	v_mfma_f32_16x16x32_bf16 v[4:7], v[168:171], v[226:229], v[4:7]
	v_mfma_f32_16x16x32_bf16 v[0:3], v[194:197], v[226:229], v[0:3]
	s_barrier
	s_add_i32 s53, s53, 2
	s_add_u32 s41, s41, 0x100
	s_addc_u32 s52, s52, 0
	s_add_u32 s46, s46, 0x100
	s_addc_u32 s47, s47, 0
	s_cmp_gt_u32 s53, 13
	s_cbranch_scc0 .LBB0_659
	s_and_b64 vcc, exec, s[16:17]
	s_cbranch_vccz .LBB0_662
	s_barrier

; #define PG8_STAGE(bufoff, gbase, voff) do { _Pragma("unroll") for (int _i = 0; _i < 2; ++_i) \
;         __builtin_amdgcn_global_load_lds((const unsigned*)((const char*)(gbase) + (voff)[_i]), (PG8_LAS unsigned*)(lds + (bufoff) + ldsw + _i * 8192), 16, 0, 0); } while (0)
; #define PG8_LDA(dst, b, h) do { _Pragma("unroll") for (int m = 0; m < 4; ++m) _Pragma("unroll") for (int k = 0; k < 2; ++k) dst[m][k] = *(const PG8_LAS bf16x8*)(lds + PG8_SA(b, h) + aoff + m * 2048 + k * 1024); } while (0)
; #define PG8_LDB(dst, b, h) do { _Pragma("unroll") for (int n = 0; n < 2; ++n) _Pragma("unroll") for (int k = 0; k < 2; ++k) dst[n][k] = *(const PG8_LAS bf16x8*)(lds + PG8_SB(b, h) + boff + n * 2048 + k * 1024); } while (0)
; #define PG8_WAIT_V(n) asm volatile("s_waitcnt vmcnt(" #n ")" ::: "memory")
; #define PG8_WAIT_L(n) asm volatile("s_waitcnt lgkmcnt(" #n ")" ::: "memory")
; #define PG8_BAR __builtin_amdgcn_s_barrier()
; #define PG8_SCHED __builtin_amdgcn_sched_barrier(0)
; template <class Epi, class Sched, bool ALIGN_EPI = false, bool SP2 = false>
; __device__ __forceinline__ void gemm_phase(PG8_LAS unsigned char* lds, const Gemm g, const Sched& S, const Epi& E) {
;     ...
;         const bool has_next = S.next(ui + 1, nxt);
;         const char* nA = has_next ? (const char*)g.A + (size_t)nxt.pm * tstep : cA; const char* nB = has_next ? (const char*)g.Bt + (size_t)nxt.pn * tstep : cB;
;         for (int t = 0; t < nt; t += 2) {
;             const bool last = (t == nt - 2);
;             const char* a1 = cA + (size_t)(t + 1) * kstep;
;             const char* a2 = last ? nA : cA + (size_t)(t + 2) * kstep; const char* b2 = last ? nB : cB + (size_t)(t + 2) * kstep;
;             const char* a3 = a2 + kstep; const char* b3 = b2 + kstep;
;             if (last && has_next) S.a_ready(nxt);
;             if constexpr (SP2) {
;             PG8_LDB(B0, 0, 0); PG8_LDB(B1, 0, 1); PG8_SCHED; PG8_LDA(At, 0, 0); PG8_STAGE(PG8_SA(1, 1), a1 + hstep, voffA);
;             PG8_WAIT_V(8); PG8_WAIT_L(0); PG8_BAR; PG8_MMA(0, 0, At, B0); PG8_MMA(0, 1, At, B1); PG8_BAR; PG8_SCHED;
;             PG8_LDA(At, 0, 1); PG8_STAGE(PG8_SB(0, 0), b2, voffB); PG8_STAGE(PG8_SB(0, 1), b2 + hstep, voffB); PG8_STAGE(PG8_SA(0, 0), a2, voffA);
;             PG8_WAIT_V(8); PG8_WAIT_L(0); PG8_BAR; PG8_MMA(1, 0, At, B0); PG8_MMA(1, 1, At, B1); PG8_BAR; PG8_SCHED;
.LBB0_744:
	s_add_u32 s38, s4, 0xfff00080
	s_addc_u32 s39, s5, -1
	s_add_i32 s60, 0, 0x10000
	s_cmp_eq_u32 s59, 60
	s_cselect_b32 s57, s33, s39
	s_cselect_b32 s56, s34, s38
	s_cselect_b32 s39, s35, s58
	s_cselect_b32 s38, s49, s51
	s_add_i32 s62, 0, 0x14000
	v_add_u32_e32 v140, s60, v205
	v_add_u32_e32 v168, s62, v205
	ds_read_b128 v[120:123], v140
	ds_read_b128 v[132:135], v140 offset:1024
	ds_read_b128 v[136:139], v140 offset:2048
	ds_read_b128 v[140:143], v140 offset:3072
	ds_read_b128 v[144:147], v168
	ds_read_b128 v[148:151], v168 offset:1024
	ds_read_b128 v[152:155], v168 offset:2048
	ds_read_b128 v[168:171], v168 offset:3072
	v_lshl_add_u64 v[178:179], s[4:5], 0, v[166:167]
	s_add_i32 m0, s21, 0xc000
	ds_read_b128 v[172:175], v207
	ds_read_b128 v[194:197], v207 offset:1024
	ds_read_b128 v[198:201], v207 offset:2048
	ds_read_b128 v[208:211], v207 offset:3072
	ds_read_b128 v[212:215], v207 offset:4096
	ds_read_b128 v[216:219], v207 offset:5120
	ds_read_b128 v[220:223], v207 offset:6144
	ds_read_b128 v[224:227], v207 offset:7168
	global_load_lds_dwordx4 v[178:179], off
	v_lshl_add_u64 v[178:179], s[4:5], 0, v[164:165]
	s_add_i32 m0, s21, 0xe000
	s_nop 0
	global_load_lds_dwordx4 v[178:179], off
	s_waitcnt vmcnt(8)
	s_waitcnt lgkmcnt(0)
	s_barrier
	s_waitcnt lgkmcnt(0)
	v_mfma_f32_16x16x32_bf16 v[128:131], v[120:123], v[172:175], v[128:131]
	v_mfma_f32_16x16x32_bf16 v[124:127], v[136:139], v[172:175], v[124:127]
	v_mfma_f32_16x16x32_bf16 v[108:111], v[120:123], v[198:201], v[108:111]
	v_mfma_f32_16x16x32_bf16 v[104:107], v[136:139], v[198:201], v[104:107]
	v_mfma_f32_16x16x32_bf16 v[92:95], v[120:123], v[212:215], v[92:95]
	v_mfma_f32_16x16x32_bf16 v[88:91], v[136:139], v[212:215], v[88:91]
	v_mfma_f32_16x16x32_bf16 v[76:79], v[120:123], v[220:223], v[76:79]
	v_mfma_f32_16x16x32_bf16 v[72:75], v[136:139], v[220:223], v[72:75]
	v_mfma_f32_16x16x32_bf16 v[128:131], v[132:135], v[194:197], v[128:131]
	v_mfma_f32_16x16x32_bf16 v[124:127], v[140:143], v[194:197], v[124:127]
	v_mfma_f32_16x16x32_bf16 v[108:111], v[132:135], v[208:211], v[108:111]
	v_mfma_f32_16x16x32_bf16 v[104:107], v[140:143], v[208:211], v[104:107]
	v_mfma_f32_16x16x32_bf16 v[92:95], v[132:135], v[216:219], v[92:95]
	v_mfma_f32_16x16x32_bf16 v[88:91], v[140:143], v[216:219], v[88:91]
	v_mfma_f32_16x16x32_bf16 v[76:79], v[132:135], v[224:227], v[76:79]
	v_mfma_f32_16x16x32_bf16 v[72:75], v[140:143], v[224:227], v[72:75]
	v_mfma_f32_16x16x32_bf16 v[116:119], v[144:147], v[172:175], v[116:119]
	v_mfma_f32_16x16x32_bf16 v[112:115], v[152:155], v[172:175], v[112:115]
	v_mfma_f32_16x16x32_bf16 v[100:103], v[144:147], v[198:201], v[100:103]
	v_mfma_f32_16x16x32_bf16 v[96:99], v[152:155], v[198:201], v[96:99]
	v_mfma_f32_16x16x32_bf16 v[84:87], v[144:147], v[212:215], v[84:87]
	v_mfma_f32_16x16x32_bf16 v[80:83], v[152:155], v[212:215], v[80:83]
	v_mfma_f32_16x16x32_bf16 v[68:71], v[144:147], v[220:223], v[68:71]
	v_mfma_f32_16x16x32_bf16 v[64:67], v[152:155], v[220:223], v[64:67]
	v_mfma_f32_16x16x32_bf16 v[116:119], v[148:151], v[194:197], v[116:119]
	v_mfma_f32_16x16x32_bf16 v[112:115], v[168:171], v[194:197], v[112:115]
	v_mfma_f32_16x16x32_bf16 v[100:103], v[148:151], v[208:211], v[100:103]
	v_mfma_f32_16x16x32_bf16 v[96:99], v[168:171], v[208:211], v[96:99]
	v_mfma_f32_16x16x32_bf16 v[84:87], v[148:151], v[216:219], v[84:87]
	v_mfma_f32_16x16x32_bf16 v[80:83], v[168:171], v[216:219], v[80:83]
	v_mfma_f32_16x16x32_bf16 v[68:71], v[148:151], v[224:227], v[68:71]
	v_mfma_f32_16x16x32_bf16 v[64:67], v[168:171], v[224:227], v[64:67]
	s_barrier
	s_add_i32 s60, s60, s20
	v_lshl_add_u64 v[178:179], s[38:39], 0, v[160:161]
	s_mov_b32 m0, s60
	ds_read_b128 v[172:175], v207 offset:16384
	ds_read_b128 v[194:197], v207 offset:17408
	ds_read_b128 v[198:201], v207 offset:18432
	ds_read_b128 v[208:211], v207 offset:19456
	ds_read_b128 v[212:215], v207 offset:20480
	ds_read_b128 v[216:219], v207 offset:21504
	ds_read_b128 v[220:223], v207 offset:22528
	ds_read_b128 v[224:227], v207 offset:23552
	global_load_lds_dwordx4 v[178:179], off
	s_add_i32 m0, s60, 0x2000
	s_add_u32 s60, s38, 0x100000
	v_lshl_add_u64 v[202:203], s[38:39], 0, v[156:157]
	s_addc_u32 s61, s39, 0
	s_add_i32 s62, s62, s20
	global_load_lds_dwordx4 v[202:203], off
	v_lshl_add_u64 v[228:229], s[60:61], 0, v[160:161]
	s_mov_b32 m0, s62
	v_lshl_add_u64 v[230:231], s[56:57], 0, v[158:159]
	global_load_lds_dwordx4 v[228:229], off
	v_lshl_add_u64 v[228:229], s[60:61], 0, v[156:157]
	s_add_i32 m0, s62, 0x2000
	s_nop 0
	global_load_lds_dwordx4 v[228:229], off
	v_lshl_add_u64 v[228:229], s[56:57], 0, v[162:163]
	s_mov_b32 m0, s21
	s_nop 0
	global_load_lds_dwordx4 v[228:229], off
	s_mov_b32 m0, s22
	s_nop 0
	global_load_lds_dwordx4 v[230:231], off
	s_waitcnt vmcnt(8)
	s_waitcnt lgkmcnt(0)
	s_barrier
; #define PG8_STAGE(bufoff, gbase, voff) do { _Pragma("unroll") for (int _i = 0; _i < 2; ++_i) \
;         __builtin_amdgcn_global_load_lds((const unsigned*)((const char*)(gbase) + (voff)[_i]), (PG8_LAS unsigned*)(lds + (bufoff) + ldsw + _i * 8192), 16, 0, 0); } while (0)
; #define PG8_LDA(dst, b, h) do { _Pragma("unroll") for (int m = 0; m < 4; ++m) _Pragma("unroll") for (int k = 0; k < 2; ++k) dst[m][k] = *(const PG8_LAS bf16x8*)(lds + PG8_SA(b, h) + aoff + m * 2048 + k * 1024); } while (0)
; #define PG8_LDB(dst, b, h) do { _Pragma("unroll") for (int n = 0; n < 2; ++n) _Pragma("unroll") for (int k = 0; k < 2; ++k) dst[n][k] = *(const PG8_LAS bf16x8*)(lds + PG8_SB(b, h) + boff + n * 2048 + k * 1024); } while (0)
; #define PG8_MMA(ai, bj, At, Bt) do { __builtin_amdgcn_s_setprio(1); _Pragma("unroll") for (int m = 0; m < 4; ++m) _Pragma("unroll") for (int n = 0; n < 2; ++n) _Pragma("unroll") for (int k = 0; k < 2; ++k) \
;         acc[ai][bj][m][n] = __builtin_amdgcn_mfma_f32_16x16x32_bf16(Bt[n][k], At[m][k], acc[ai][bj][m][n], 0, 0, 0); __builtin_amdgcn_s_setprio(0); } while (0)
; #define PG8_WAIT_V(n) asm volatile("s_waitcnt vmcnt(" #n ")" ::: "memory")
; #define PG8_WAIT_L(n) asm volatile("s_waitcnt lgkmcnt(" #n ")" ::: "memory")
; #define PG8_BAR __builtin_amdgcn_s_barrier()
; #define PG8_SCHED __builtin_amdgcn_sched_barrier(0)
; template <class Epi, class Sched, bool ALIGN_EPI = false, bool SP2 = false>
; __device__ __forceinline__ void gemm_phase(PG8_LAS unsigned char* lds, const Gemm g, const Sched& S, const Epi& E) {
;     ...
;             PG8_WAIT_V(8); PG8_WAIT_L(0); PG8_BAR; PG8_MMA(1, 0, At, B0); PG8_MMA(1, 1, At, B1); PG8_BAR; PG8_SCHED;
;             PG8_LDB(B0, 1, 0); PG8_LDB(B1, 1, 1); PG8_SCHED; PG8_LDA(At, 1, 0); PG8_STAGE(PG8_SA(0, 1), a2 + hstep, voffA);
;             PG8_WAIT_V(8); PG8_WAIT_L(0); PG8_BAR; PG8_MMA(0, 0, At, B0); PG8_MMA(0, 1, At, B1); PG8_BAR; PG8_SCHED;
;             PG8_LDA(At, 1, 1); PG8_STAGE(PG8_SB(1, 0), b3, voffB); PG8_STAGE(PG8_SB(1, 1), b3 + hstep, voffB); PG8_STAGE(PG8_SA(1, 0), a3, voffA);
	s_waitcnt lgkmcnt(0)
	v_mfma_f32_16x16x32_bf16 v[60:63], v[120:123], v[172:175], v[60:63]
	v_mfma_f32_16x16x32_bf16 v[56:59], v[136:139], v[172:175], v[56:59]
	v_mfma_f32_16x16x32_bf16 v[44:47], v[120:123], v[198:201], v[44:47]
	v_mfma_f32_16x16x32_bf16 v[40:43], v[136:139], v[198:201], v[40:43]
	v_mfma_f32_16x16x32_bf16 v[28:31], v[120:123], v[212:215], v[28:31]
	v_mfma_f32_16x16x32_bf16 v[24:27], v[136:139], v[212:215], v[24:27]
	v_mfma_f32_16x16x32_bf16 v[12:15], v[120:123], v[220:223], v[12:15]
	v_mfma_f32_16x16x32_bf16 v[8:11], v[136:139], v[220:223], v[8:11]
	v_mfma_f32_16x16x32_bf16 v[60:63], v[132:135], v[194:197], v[60:63]
	v_mfma_f32_16x16x32_bf16 v[56:59], v[140:143], v[194:197], v[56:59]
	v_mfma_f32_16x16x32_bf16 v[44:47], v[132:135], v[208:211], v[44:47]
	v_mfma_f32_16x16x32_bf16 v[40:43], v[140:143], v[208:211], v[40:43]
	v_mfma_f32_16x16x32_bf16 v[28:31], v[132:135], v[216:219], v[28:31]
	v_mfma_f32_16x16x32_bf16 v[24:27], v[140:143], v[216:219], v[24:27]
	v_mfma_f32_16x16x32_bf16 v[12:15], v[132:135], v[224:227], v[12:15]
	v_mfma_f32_16x16x32_bf16 v[8:11], v[140:143], v[224:227], v[8:11]
	v_mfma_f32_16x16x32_bf16 v[52:55], v[144:147], v[172:175], v[52:55]
	v_mfma_f32_16x16x32_bf16 v[48:51], v[152:155], v[172:175], v[48:51]
	v_mfma_f32_16x16x32_bf16 v[36:39], v[144:147], v[198:201], v[36:39]
	v_mfma_f32_16x16x32_bf16 v[32:35], v[152:155], v[198:201], v[32:35]
	v_mfma_f32_16x16x32_bf16 v[20:23], v[144:147], v[212:215], v[20:23]
	v_mfma_f32_16x16x32_bf16 v[16:19], v[152:155], v[212:215], v[16:19]
	v_mfma_f32_16x16x32_bf16 v[4:7], v[144:147], v[220:223], v[4:7]
	v_mfma_f32_16x16x32_bf16 v[0:3], v[152:155], v[220:223], v[0:3]
	v_mfma_f32_16x16x32_bf16 v[52:55], v[148:151], v[194:197], v[52:55]
	v_mfma_f32_16x16x32_bf16 v[48:51], v[168:171], v[194:197], v[48:51]
	v_mfma_f32_16x16x32_bf16 v[36:39], v[148:151], v[208:211], v[36:39]
	v_mfma_f32_16x16x32_bf16 v[32:35], v[168:171], v[208:211], v[32:35]
	v_mfma_f32_16x16x32_bf16 v[20:23], v[148:151], v[216:219], v[20:23]
	v_mfma_f32_16x16x32_bf16 v[16:19], v[168:171], v[216:219], v[16:19]
	v_mfma_f32_16x16x32_bf16 v[4:7], v[148:151], v[224:227], v[4:7]
	v_mfma_f32_16x16x32_bf16 v[0:3], v[168:171], v[224:227], v[0:3]
	s_barrier
	s_add_i32 s60, 0, 0x18000
	s_add_i32 s61, 0, 0x1c000
	v_add_u32_e32 v140, s60, v205
	v_add_u32_e32 v168, s61, v205
	ds_read_b128 v[120:123], v140
	ds_read_b128 v[132:135], v140 offset:1024
	ds_read_b128 v[136:139], v140 offset:2048
	ds_read_b128 v[140:143], v140 offset:3072
	ds_read_b128 v[144:147], v168
	ds_read_b128 v[148:151], v168 offset:1024
	ds_read_b128 v[152:155], v168 offset:2048
	ds_read_b128 v[168:171], v168 offset:3072
	s_add_u32 s56, s56, 0x100000
	s_addc_u32 s57, s57, 0
	s_mov_b32 m0, s23
	v_lshl_add_u64 v[232:233], s[56:57], 0, v[162:163]
	ds_read_b128 v[172:175], v207 offset:32768
	ds_read_b128 v[194:197], v207 offset:33792
	ds_read_b128 v[198:201], v207 offset:34816
	ds_read_b128 v[208:211], v207 offset:35840
	ds_read_b128 v[212:215], v207 offset:36864
	ds_read_b128 v[216:219], v207 offset:37888
	ds_read_b128 v[220:223], v207 offset:38912
	ds_read_b128 v[224:227], v207 offset:39936
	global_load_lds_dwordx4 v[232:233], off
	v_lshl_add_u64 v[232:233], s[56:57], 0, v[158:159]
	s_mov_b32 m0, s24
	s_nop 0
	global_load_lds_dwordx4 v[232:233], off
	s_waitcnt vmcnt(8)
	s_waitcnt lgkmcnt(0)
	s_barrier
	s_waitcnt lgkmcnt(0)
	v_mfma_f32_16x16x32_bf16 v[128:131], v[120:123], v[172:175], v[128:131]
	v_mfma_f32_16x16x32_bf16 v[124:127], v[136:139], v[172:175], v[124:127]
	v_mfma_f32_16x16x32_bf16 v[108:111], v[120:123], v[198:201], v[108:111]
	v_mfma_f32_16x16x32_bf16 v[104:107], v[136:139], v[198:201], v[104:107]
	v_mfma_f32_16x16x32_bf16 v[92:95], v[120:123], v[212:215], v[92:95]
	v_mfma_f32_16x16x32_bf16 v[88:91], v[136:139], v[212:215], v[88:91]
	v_mfma_f32_16x16x32_bf16 v[76:79], v[120:123], v[220:223], v[76:79]
	v_mfma_f32_16x16x32_bf16 v[72:75], v[136:139], v[220:223], v[72:75]
	v_mfma_f32_16x16x32_bf16 v[128:131], v[132:135], v[194:197], v[128:131]
	v_mfma_f32_16x16x32_bf16 v[124:127], v[140:143], v[194:197], v[124:127]
	v_mfma_f32_16x16x32_bf16 v[108:111], v[132:135], v[208:211], v[108:111]
	v_mfma_f32_16x16x32_bf16 v[104:107], v[140:143], v[208:211], v[104:107]
	v_mfma_f32_16x16x32_bf16 v[92:95], v[132:135], v[216:219], v[92:95]
	v_mfma_f32_16x16x32_bf16 v[88:91], v[140:143], v[216:219], v[88:91]
	v_mfma_f32_16x16x32_bf16 v[76:79], v[132:135], v[224:227], v[76:79]
	v_mfma_f32_16x16x32_bf16 v[72:75], v[140:143], v[224:227], v[72:75]
	v_mfma_f32_16x16x32_bf16 v[116:119], v[144:147], v[172:175], v[116:119]
	v_mfma_f32_16x16x32_bf16 v[112:115], v[152:155], v[172:175], v[112:115]
	v_mfma_f32_16x16x32_bf16 v[100:103], v[144:147], v[198:201], v[100:103]
	v_mfma_f32_16x16x32_bf16 v[96:99], v[152:155], v[198:201], v[96:99]
	v_mfma_f32_16x16x32_bf16 v[84:87], v[144:147], v[212:215], v[84:87]
	v_mfma_f32_16x16x32_bf16 v[80:83], v[152:155], v[212:215], v[80:83]
	v_mfma_f32_16x16x32_bf16 v[68:71], v[144:147], v[220:223], v[68:71]
	v_mfma_f32_16x16x32_bf16 v[64:67], v[152:155], v[220:223], v[64:67]
	v_mfma_f32_16x16x32_bf16 v[116:119], v[148:151], v[194:197], v[116:119]
	v_mfma_f32_16x16x32_bf16 v[112:115], v[168:171], v[194:197], v[112:115]
	v_mfma_f32_16x16x32_bf16 v[100:103], v[148:151], v[208:211], v[100:103]
	v_mfma_f32_16x16x32_bf16 v[96:99], v[168:171], v[208:211], v[96:99]
	v_mfma_f32_16x16x32_bf16 v[84:87], v[148:151], v[216:219], v[84:87]
	v_mfma_f32_16x16x32_bf16 v[80:83], v[168:171], v[216:219], v[80:83]
	v_mfma_f32_16x16x32_bf16 v[68:71], v[148:151], v[224:227], v[68:71]
	v_mfma_f32_16x16x32_bf16 v[64:67], v[168:171], v[224:227], v[64:67]
	s_barrier
; #define PG8_STAGE(bufoff, gbase, voff) do { _Pragma("unroll") for (int _i = 0; _i < 2; ++_i) \
;         __builtin_amdgcn_global_load_lds((const unsigned*)((const char*)(gbase) + (voff)[_i]), (PG8_LAS unsigned*)(lds + (bufoff) + ldsw + _i * 8192), 16, 0, 0); } while (0)
; #define PG8_LDA(dst, b, h) do { _Pragma("unroll") for (int m = 0; m < 4; ++m) _Pragma("unroll") for (int k = 0; k < 2; ++k) dst[m][k] = *(const PG8_LAS bf16x8*)(lds + PG8_SA(b, h) + aoff + m * 2048 + k * 1024); } while (0)
; #define PG8_MMA(ai, bj, At, Bt) do { __builtin_amdgcn_s_setprio(1); _Pragma("unroll") for (int m = 0; m < 4; ++m) _Pragma("unroll") for (int n = 0; n < 2; ++n) _Pragma("unroll") for (int k = 0; k < 2; ++k) \
;         acc[ai][bj][m][n] = __builtin_amdgcn_mfma_f32_16x16x32_bf16(Bt[n][k], At[m][k], acc[ai][bj][m][n], 0, 0, 0); __builtin_amdgcn_s_setprio(0); } while (0)
; #define PG8_WAIT_V(n) asm volatile("s_waitcnt vmcnt(" #n ")" ::: "memory")
; #define PG8_WAIT_L(n) asm volatile("s_waitcnt lgkmcnt(" #n ")" ::: "memory")
; #define PG8_BAR __builtin_amdgcn_s_barrier()
; #define PG8_SCHED __builtin_amdgcn_sched_barrier(0)
; template <class Epi, class Sched, bool ALIGN_EPI = false, bool SP2 = false>
; __device__ __forceinline__ void gemm_phase(PG8_LAS unsigned char* lds, const Gemm g, const Sched& S, const Epi& E) {
;     ...
;             PG8_LDA(At, 1, 1); PG8_STAGE(PG8_SB(1, 0), b3, voffB); PG8_STAGE(PG8_SB(1, 1), b3 + hstep, voffB); PG8_STAGE(PG8_SA(1, 0), a3, voffA);
;             PG8_WAIT_V(8); PG8_WAIT_L(0); PG8_BAR; PG8_MMA(1, 0, At, B0); PG8_MMA(1, 1, At, B1); PG8_BAR; PG8_SCHED;
;     ...
;         if constexpr (ALIGN_EPI) { if (wr == 0) PG8_BAR; }
	s_add_i32 s56, s60, s20
	v_lshl_add_u64 v[178:179], v[178:179], 0, s[36:37]
	s_mov_b32 m0, s56
	ds_read_b128 v[172:175], v207 offset:49152
	ds_read_b128 v[194:197], v207 offset:50176
	ds_read_b128 v[198:201], v207 offset:51200
	ds_read_b128 v[208:211], v207 offset:52224
	ds_read_b128 v[212:215], v207 offset:53248
	ds_read_b128 v[216:219], v207 offset:54272
	ds_read_b128 v[220:223], v207 offset:55296
	ds_read_b128 v[224:227], v207 offset:56320
	global_load_lds_dwordx4 v[178:179], off
	s_add_i32 m0, s56, 0x2000
	s_add_u32 s38, s38, 0x100080
	v_lshl_add_u64 v[178:179], v[202:203], 0, s[36:37]
	s_addc_u32 s39, s39, 0
	s_add_i32 s56, s61, s20
	global_load_lds_dwordx4 v[178:179], off
	v_lshl_add_u64 v[178:179], s[38:39], 0, v[160:161]
	s_mov_b32 m0, s56
	s_nop 0
	global_load_lds_dwordx4 v[178:179], off
	v_lshl_add_u64 v[178:179], s[38:39], 0, v[156:157]
	s_add_i32 m0, s56, 0x2000
	s_nop 0
	global_load_lds_dwordx4 v[178:179], off
	v_lshl_add_u64 v[178:179], v[228:229], 0, s[36:37]
	s_mov_b32 m0, s29
	s_nop 0
	global_load_lds_dwordx4 v[178:179], off
	v_lshl_add_u64 v[178:179], v[230:231], 0, s[36:37]
	s_mov_b32 m0, s30
	s_nop 0
	global_load_lds_dwordx4 v[178:179], off
	s_waitcnt vmcnt(8)
	s_waitcnt lgkmcnt(0)
	s_barrier
	s_waitcnt lgkmcnt(0)
	v_mfma_f32_16x16x32_bf16 v[60:63], v[120:123], v[172:175], v[60:63]
	v_mfma_f32_16x16x32_bf16 v[56:59], v[136:139], v[172:175], v[56:59]
	v_mfma_f32_16x16x32_bf16 v[44:47], v[120:123], v[198:201], v[44:47]
	v_mfma_f32_16x16x32_bf16 v[40:43], v[136:139], v[198:201], v[40:43]
	v_mfma_f32_16x16x32_bf16 v[28:31], v[120:123], v[212:215], v[28:31]
	v_mfma_f32_16x16x32_bf16 v[24:27], v[136:139], v[212:215], v[24:27]
	v_mfma_f32_16x16x32_bf16 v[12:15], v[120:123], v[220:223], v[12:15]
	v_mfma_f32_16x16x32_bf16 v[8:11], v[136:139], v[220:223], v[8:11]
	v_mfma_f32_16x16x32_bf16 v[60:63], v[132:135], v[194:197], v[60:63]
	v_mfma_f32_16x16x32_bf16 v[56:59], v[140:143], v[194:197], v[56:59]
	v_mfma_f32_16x16x32_bf16 v[44:47], v[132:135], v[208:211], v[44:47]
	v_mfma_f32_16x16x32_bf16 v[40:43], v[140:143], v[208:211], v[40:43]
	v_mfma_f32_16x16x32_bf16 v[28:31], v[132:135], v[216:219], v[28:31]
	v_mfma_f32_16x16x32_bf16 v[24:27], v[140:143], v[216:219], v[24:27]
	v_mfma_f32_16x16x32_bf16 v[12:15], v[132:135], v[224:227], v[12:15]
	v_mfma_f32_16x16x32_bf16 v[8:11], v[140:143], v[224:227], v[8:11]
	v_mfma_f32_16x16x32_bf16 v[52:55], v[144:147], v[172:175], v[52:55]
	v_mfma_f32_16x16x32_bf16 v[48:51], v[152:155], v[172:175], v[48:51]
	v_mfma_f32_16x16x32_bf16 v[36:39], v[144:147], v[198:201], v[36:39]
	v_mfma_f32_16x16x32_bf16 v[32:35], v[152:155], v[198:201], v[32:35]
	v_mfma_f32_16x16x32_bf16 v[20:23], v[144:147], v[212:215], v[20:23]
	v_mfma_f32_16x16x32_bf16 v[16:19], v[152:155], v[212:215], v[16:19]
	v_mfma_f32_16x16x32_bf16 v[4:7], v[144:147], v[220:223], v[4:7]
	v_mfma_f32_16x16x32_bf16 v[0:3], v[152:155], v[220:223], v[0:3]
	v_mfma_f32_16x16x32_bf16 v[52:55], v[148:151], v[194:197], v[52:55]
	v_mfma_f32_16x16x32_bf16 v[48:51], v[168:171], v[194:197], v[48:51]
	v_mfma_f32_16x16x32_bf16 v[36:39], v[148:151], v[208:211], v[36:39]
	v_mfma_f32_16x16x32_bf16 v[32:35], v[168:171], v[208:211], v[32:35]
	v_mfma_f32_16x16x32_bf16 v[20:23], v[148:151], v[216:219], v[20:23]
	v_mfma_f32_16x16x32_bf16 v[16:19], v[168:171], v[216:219], v[16:19]
	v_mfma_f32_16x16x32_bf16 v[4:7], v[148:151], v[224:227], v[4:7]
	v_mfma_f32_16x16x32_bf16 v[0:3], v[168:171], v[224:227], v[0:3]
	s_barrier
	s_add_i32 s59, s59, 2
	s_add_u32 s51, s51, 0x100
	s_addc_u32 s58, s58, 0
	s_add_u32 s4, s4, 0x100
	s_addc_u32 s5, s5, 0
	s_cmp_gt_u32 s59, 61
	s_cbranch_scc0 .LBB0_744
	s_and_b64 vcc, exec, s[42:43]
	s_cbranch_vccz .LBB0_747
	s_barrier
